# merge_rows with 8 row pairs in flight (was 4); otherwise identical to v46
# speedup vs baseline: 1.0031x; 1.0031x over previous
; __device__ __forceinline__ float bf_lo(unsigned w) { return __uint_as_float(w << 16); }
; __device__ __forceinline__ float bf_hi(unsigned w) { return __uint_as_float(w & 0xffff0000u); }
; __device__ __forceinline__ unsigned pk2(float lo, float hi) { return pg8::cvt_pk_bf16(lo, hi); }
; __device__ __forceinline__ void merge_rows(const Args& a, int gw, int NGW, int lane) {
;     const bf16* OG = (const bf16*)(a.ws + WS_OG); const float* LSE = (const float*)(a.ws + WS_LSE); bf16* YAT = (bf16*)(a.ws + WS_YAT);
;     const int hh = lane >> 4;
;     for (int mb = gw; mb < MT; mb += 4 * NGW) {
;         float l[4][3]; v2u o[4][3];
; #pragma unroll
;         for (int r = 0; r < 4; ++r) { const int m = mb + r * NGW; const int mc = m < MT ? m : mb;
; #pragma unroll
;             for (int g = 0; g < 3; ++g) { l[r][g] = LSE[((size_t)g * MT + mc) * 4 + hh]; o[r][g] = *(const v2u*)(OG + ((size_t)g * MT + mc) * 256 + 4 * lane); } }
; #pragma unroll
;         for (int r = 0; r < 4; ++r) { const int m = mb + r * NGW; if (m < MT) {
;             const float mxl = fmaxf(l[r][0], fmaxf(l[r][1], l[r][2]));
;             float a0 = __expf(l[r][0] - mxl), a1 = __expf(l[r][1] - mxl), a2 = __expf(l[r][2] - mxl); const float is = 1.0f / (a0 + a1 + a2); a0 *= is; a1 *= is; a2 *= is;
;             const v2u o0 = o[r][0], o1 = o[r][1], o2 = o[r][2];
;             v2u w;
;             w.x = pk2(a0 * pg8::bf_lo(o0.x) + a1 * pg8::bf_lo(o1.x) + a2 * pg8::bf_lo(o2.x), a0 * pg8::bf_hi(o0.x) + a1 * pg8::bf_hi(o1.x) + a2 * pg8::bf_hi(o2.x));
;             w.y = pk2(a0 * pg8::bf_lo(o0.y) + a1 * pg8::bf_lo(o1.y) + a2 * pg8::bf_lo(o2.y), a0 * pg8::bf_hi(o0.y) + a1 * pg8::bf_hi(o1.y) + a2 * pg8::bf_hi(o2.y));
;             *(v2u*)(YAT + (size_t)m * 256 + 4 * lane) = w; } }
.LBB0_457:
	s_cmp_lt_i32 s78, 5
	s_cselect_b64 s[2:3], -1, 0
	s_and_b64 s[10:11], s[2:3], s[0:1]
	s_andn2_b64 vcc, exec, s[10:11]
	s_cbranch_vccnz .LBB0_613
	s_mov_b64 s[0:1], s[72:73]
	s_load_dwordx4 s[12:15], s[0:1], 0xe0
	v_mov_b32_e32 v0, v254
	s_lshl_b32 s2, s96, 3
	v_readfirstlane_b32 s0, v0
	s_ashr_i32 s0, s0, 6
	s_add_i32 s18, s0, s2
	s_cmp_gt_i32 s18, 0x17fff
	s_cbranch_scc1 .LBB0_467
	s_cmp_eq_u32 s70, 0x100
	s_cbranch_scc0 .Lorig_merge
	v_and_b32_e32 v130, 63, v254
	v_lshrrev_b32_e32 v128, 5, v130
	v_and_b32_e32 v130, 31, v130
	v_lshlrev_b32_e32 v129, 15, v128
	v_lshlrev_b32_e32 v128, 20, v128
	v_lshl_add_u32 v128, v130, 4, v128
	v_lshrrev_b32_e32 v130, 3, v130
	v_lshl_add_u32 v129, v130, 2, v129
	v_readfirstlane_b32 s16, v254
	s_nop 3
	s_lshl_b32 s17, s96, 3
	s_lshr_b32 s16, s16, 6
	s_add_i32 s16, s16, s17
	s_waitcnt lgkmcnt(0)
	s_mov_b64 s[6:7], s[14:15]
	s_lshl_b32 s17, s16, 9
	s_add_u32 s20, s6, s17
	s_addc_u32 s21, s7, 0
	s_add_u32 s20, s20, 0x2a000000
	s_addc_u32 s21, s21, 0
	s_add_u32 s24, s6, s17
	s_addc_u32 s25, s7, 0
	s_add_u32 s24, s24, 0x3c000000
	s_addc_u32 s25, s25, 0
	s_lshl_b32 s17, s16, 4
	s_add_u32 s22, s6, s17
	s_addc_u32 s23, s7, 0
	s_add_u32 s22, s22, 0x33000000
	s_addc_u32 s23, s23, 0
	s_mov_b64 s[26:27], s[20:21]
	global_load_dwordx4 v[0:3], v128, s[26:27]
	s_add_u32 s26, s20, 0x3000000
	s_addc_u32 s27, s21, 0
	global_load_dwordx4 v[4:7], v128, s[26:27]
	s_add_u32 s26, s20, 0x6000000
	s_addc_u32 s27, s21, 0
	global_load_dwordx4 v[8:11], v128, s[26:27]
	s_mov_b64 s[26:27], s[22:23]
	global_load_dword v12, v129, s[26:27]
	s_add_u32 s26, s22, 0x180000
	s_addc_u32 s27, s23, 0
	global_load_dword v13, v129, s[26:27]
	s_add_u32 s26, s22, 0x300000
	s_addc_u32 s27, s23, 0
	global_load_dword v14, v129, s[26:27]
	s_add_u32 s26, s20, 0x200000
	s_addc_u32 s27, s21, 0
	global_load_dwordx4 v[16:19], v128, s[26:27]
	s_add_u32 s26, s20, 0x3200000
	s_addc_u32 s27, s21, 0
	global_load_dwordx4 v[20:23], v128, s[26:27]
	s_add_u32 s26, s20, 0x6200000
	s_addc_u32 s27, s21, 0
	global_load_dwordx4 v[24:27], v128, s[26:27]
	s_add_u32 s26, s22, 0x10000
	s_addc_u32 s27, s23, 0
	global_load_dword v28, v129, s[26:27]
	s_add_u32 s26, s22, 0x190000
	s_addc_u32 s27, s23, 0
	global_load_dword v29, v129, s[26:27]
	s_add_u32 s26, s22, 0x310000
	s_addc_u32 s27, s23, 0
	global_load_dword v30, v129, s[26:27]
	s_add_u32 s26, s20, 0x400000
	s_addc_u32 s27, s21, 0
	global_load_dwordx4 v[32:35], v128, s[26:27]
	s_add_u32 s26, s20, 0x3400000
	s_addc_u32 s27, s21, 0
	global_load_dwordx4 v[36:39], v128, s[26:27]
	s_add_u32 s26, s20, 0x6400000
	s_addc_u32 s27, s21, 0
	global_load_dwordx4 v[40:43], v128, s[26:27]
	s_add_u32 s26, s22, 0x20000
	s_addc_u32 s27, s23, 0
	global_load_dword v44, v129, s[26:27]
	s_add_u32 s26, s22, 0x1a0000
	s_addc_u32 s27, s23, 0
	global_load_dword v45, v129, s[26:27]
	s_add_u32 s26, s22, 0x320000
	s_addc_u32 s27, s23, 0
	global_load_dword v46, v129, s[26:27]
	s_add_u32 s26, s20, 0x600000
	s_addc_u32 s27, s21, 0
	global_load_dwordx4 v[48:51], v128, s[26:27]
	s_add_u32 s26, s20, 0x3600000
	s_addc_u32 s27, s21, 0
	global_load_dwordx4 v[52:55], v128, s[26:27]
	s_add_u32 s26, s20, 0x6600000
	s_addc_u32 s27, s21, 0
	global_load_dwordx4 v[56:59], v128, s[26:27]
	s_add_u32 s26, s22, 0x30000
	s_addc_u32 s27, s23, 0
	global_load_dword v60, v129, s[26:27]
	s_add_u32 s26, s22, 0x1b0000
	s_addc_u32 s27, s23, 0
	global_load_dword v61, v129, s[26:27]
	s_add_u32 s26, s22, 0x330000
	s_addc_u32 s27, s23, 0
	global_load_dword v62, v129, s[26:27]
	s_add_u32 s26, s20, 0x800000
	s_addc_u32 s27, s21, 0
	global_load_dwordx4 v[64:67], v128, s[26:27]
	s_add_u32 s26, s20, 0x3800000
	s_addc_u32 s27, s21, 0
	global_load_dwordx4 v[68:71], v128, s[26:27]
	s_add_u32 s26, s20, 0x6800000
	s_addc_u32 s27, s21, 0
	global_load_dwordx4 v[72:75], v128, s[26:27]
	s_add_u32 s26, s22, 0x40000
	s_addc_u32 s27, s23, 0
	global_load_dword v76, v129, s[26:27]
	s_add_u32 s26, s22, 0x1c0000
	s_addc_u32 s27, s23, 0
	global_load_dword v77, v129, s[26:27]
	s_add_u32 s26, s22, 0x340000
	s_addc_u32 s27, s23, 0
	global_load_dword v78, v129, s[26:27]
	s_add_u32 s26, s20, 0xa00000
	s_addc_u32 s27, s21, 0
	global_load_dwordx4 v[80:83], v128, s[26:27]
	s_add_u32 s26, s20, 0x3a00000
	s_addc_u32 s27, s21, 0
	global_load_dwordx4 v[84:87], v128, s[26:27]
	s_add_u32 s26, s20, 0x6a00000
	s_addc_u32 s27, s21, 0
	global_load_dwordx4 v[88:91], v128, s[26:27]
	s_add_u32 s26, s22, 0x50000
	s_addc_u32 s27, s23, 0
	global_load_dword v92, v129, s[26:27]
	s_add_u32 s26, s22, 0x1d0000
	s_addc_u32 s27, s23, 0
	global_load_dword v93, v129, s[26:27]
	s_add_u32 s26, s22, 0x350000
	s_addc_u32 s27, s23, 0
	global_load_dword v94, v129, s[26:27]
	s_add_u32 s26, s20, 0xc00000
	s_addc_u32 s27, s21, 0
	global_load_dwordx4 v[96:99], v128, s[26:27]
	s_add_u32 s26, s20, 0x3c00000
	s_addc_u32 s27, s21, 0
	global_load_dwordx4 v[100:103], v128, s[26:27]
	s_add_u32 s26, s20, 0x6c00000
	s_addc_u32 s27, s21, 0
	global_load_dwordx4 v[104:107], v128, s[26:27]
	s_add_u32 s26, s22, 0x60000
	s_addc_u32 s27, s23, 0
	global_load_dword v108, v129, s[26:27]
	s_add_u32 s26, s22, 0x1e0000
	s_addc_u32 s27, s23, 0
	global_load_dword v109, v129, s[26:27]
	s_add_u32 s26, s22, 0x360000
	s_addc_u32 s27, s23, 0
	global_load_dword v110, v129, s[26:27]
	s_add_u32 s26, s20, 0xe00000
	s_addc_u32 s27, s21, 0
	global_load_dwordx4 v[112:115], v128, s[26:27]
	s_add_u32 s26, s20, 0x3e00000
	s_addc_u32 s27, s21, 0
	global_load_dwordx4 v[116:119], v128, s[26:27]
	s_add_u32 s26, s20, 0x6e00000
	s_addc_u32 s27, s21, 0
	global_load_dwordx4 v[120:123], v128, s[26:27]
	s_add_u32 s26, s22, 0x70000
	s_addc_u32 s27, s23, 0
	global_load_dword v124, v129, s[26:27]
	s_add_u32 s26, s22, 0x1f0000
	s_addc_u32 s27, s23, 0
	global_load_dword v125, v129, s[26:27]
	s_add_u32 s26, s22, 0x370000
	s_addc_u32 s27, s23, 0
	global_load_dword v126, v129, s[26:27]
	s_waitcnt vmcnt(42)
; __device__ __forceinline__ float bf_lo(unsigned w) { return __uint_as_float(w << 16); }
; __device__ __forceinline__ float bf_hi(unsigned w) { return __uint_as_float(w & 0xffff0000u); }
; __device__ __forceinline__ unsigned pk2(float lo, float hi) { return pg8::cvt_pk_bf16(lo, hi); }
; __device__ __forceinline__ void merge_rows(const Args& a, int gw, int NGW, int lane) {
;     ...
;         for (int r = 0; r < 4; ++r) { const int m = mb + r * NGW; const int mc = m < MT ? m : mb;
; #pragma unroll
;             for (int g = 0; g < 3; ++g) { l[r][g] = LSE[((size_t)g * MT + mc) * 4 + hh]; o[r][g] = *(const v2u*)(OG + ((size_t)g * MT + mc) * 256 + 4 * lane); } }
;     ...
;         for (int r = 0; r < 4; ++r) { const int m = mb + r * NGW; if (m < MT) {
;             const float mxl = fmaxf(l[r][0], fmaxf(l[r][1], l[r][2]));
;             float a0 = __expf(l[r][0] - mxl), a1 = __expf(l[r][1] - mxl), a2 = __expf(l[r][2] - mxl); const float is = 1.0f / (a0 + a1 + a2); a0 *= is; a1 *= is; a2 *= is;
;             const v2u o0 = o[r][0], o1 = o[r][1], o2 = o[r][2];
;             v2u w;
;             w.x = pk2(a0 * pg8::bf_lo(o0.x) + a1 * pg8::bf_lo(o1.x) + a2 * pg8::bf_lo(o2.x), a0 * pg8::bf_hi(o0.x) + a1 * pg8::bf_hi(o1.x) + a2 * pg8::bf_hi(o2.x));
;             w.y = pk2(a0 * pg8::bf_lo(o0.y) + a1 * pg8::bf_lo(o1.y) + a2 * pg8::bf_lo(o2.y), a0 * pg8::bf_hi(o0.y) + a1 * pg8::bf_hi(o1.y) + a2 * pg8::bf_hi(o2.y));
;             *(v2u*)(YAT + (size_t)m * 256 + 4 * lane) = w; } }
	v_max3_f32 v132, v12, v13, v14
	v_sub_f32_e32 v133, v12, v132
	v_sub_f32_e32 v134, v13, v132
	v_sub_f32_e32 v135, v14, v132
	v_mul_f32_e32 v133, 0x3fb8aa3b, v133
	v_mul_f32_e32 v134, 0x3fb8aa3b, v134
	v_mul_f32_e32 v135, 0x3fb8aa3b, v135
	v_exp_f32_e32 v133, v133
	v_exp_f32_e32 v134, v134
	v_exp_f32_e32 v135, v135
	s_nop 0
	v_add_f32_e32 v136, v133, v134
	v_add_f32_e32 v136, v135, v136
	v_div_scale_f32 v137, s[28:29], v136, v136, 1.0
	v_rcp_f32_e32 v138, v137
	v_div_scale_f32 v139, vcc, 1.0, v136, 1.0
	s_nop 0
	v_fma_f32 v140, -v137, v138, 1.0
	v_fmac_f32_e32 v138, v140, v138
	v_mul_f32_e32 v141, v139, v138
	v_fma_f32 v140, -v137, v141, v139
	v_fmac_f32_e32 v141, v140, v138
	v_fma_f32 v137, -v137, v141, v139
	v_div_fmas_f32 v137, v137, v138, v141
	v_div_fixup_f32 v136, v137, v136, 1.0
	v_mul_f32_e32 v133, v133, v136
	v_mul_f32_e32 v134, v134, v136
	v_mul_f32_e32 v135, v135, v136
	v_lshlrev_b32_e32 v142, 16, v0
	v_and_b32_e32 v145, 0xffff0000, v0
	v_lshlrev_b32_e32 v143, 16, v4
	v_and_b32_e32 v146, 0xffff0000, v4
	v_lshlrev_b32_e32 v144, 16, v8
	v_and_b32_e32 v147, 0xffff0000, v8
	v_mul_f32_e32 v148, v133, v142
	v_mul_f32_e32 v149, v133, v145
	v_fmac_f32_e32 v148, v134, v143
	v_fmac_f32_e32 v149, v134, v146
	v_fmac_f32_e32 v148, v135, v144
	v_fmac_f32_e32 v149, v135, v147
	v_cvt_pk_bf16_f32 v160, v148, v149
	v_lshlrev_b32_e32 v142, 16, v1
	v_and_b32_e32 v145, 0xffff0000, v1
	v_lshlrev_b32_e32 v143, 16, v5
	v_and_b32_e32 v146, 0xffff0000, v5
	v_lshlrev_b32_e32 v144, 16, v9
	v_and_b32_e32 v147, 0xffff0000, v9
	v_mul_f32_e32 v148, v133, v142
	v_mul_f32_e32 v149, v133, v145
	v_fmac_f32_e32 v148, v134, v143
	v_fmac_f32_e32 v149, v134, v146
	v_fmac_f32_e32 v148, v135, v144
	v_fmac_f32_e32 v149, v135, v147
	v_cvt_pk_bf16_f32 v161, v148, v149
	v_lshlrev_b32_e32 v142, 16, v2
	v_and_b32_e32 v145, 0xffff0000, v2
	v_lshlrev_b32_e32 v143, 16, v6
	v_and_b32_e32 v146, 0xffff0000, v6
	v_lshlrev_b32_e32 v144, 16, v10
	v_and_b32_e32 v147, 0xffff0000, v10
	v_mul_f32_e32 v148, v133, v142
	v_mul_f32_e32 v149, v133, v145
	v_fmac_f32_e32 v148, v134, v143
	v_fmac_f32_e32 v149, v134, v146
	v_fmac_f32_e32 v148, v135, v144
	v_fmac_f32_e32 v149, v135, v147
	v_cvt_pk_bf16_f32 v162, v148, v149
	v_lshlrev_b32_e32 v142, 16, v3
	v_and_b32_e32 v145, 0xffff0000, v3
	v_lshlrev_b32_e32 v143, 16, v7
	v_and_b32_e32 v146, 0xffff0000, v7
	v_lshlrev_b32_e32 v144, 16, v11
	v_and_b32_e32 v147, 0xffff0000, v11
	v_mul_f32_e32 v148, v133, v142
	v_mul_f32_e32 v149, v133, v145
	v_fmac_f32_e32 v148, v134, v143
	v_fmac_f32_e32 v149, v134, v146
	v_fmac_f32_e32 v148, v135, v144
	v_fmac_f32_e32 v149, v135, v147
	v_cvt_pk_bf16_f32 v163, v148, v149
	s_mov_b64 s[26:27], s[24:25]
	global_store_dwordx4 v128, v[160:163], s[26:27]
	s_add_u32 s26, s20, 0x1000000
	s_addc_u32 s27, s21, 0
	global_load_dwordx4 v[0:3], v128, s[26:27]
	s_add_u32 s26, s20, 0x4000000
	s_addc_u32 s27, s21, 0
	global_load_dwordx4 v[4:7], v128, s[26:27]
	s_add_u32 s26, s20, 0x7000000
	s_addc_u32 s27, s21, 0
	global_load_dwordx4 v[8:11], v128, s[26:27]
	s_add_u32 s26, s22, 0x80000
	s_addc_u32 s27, s23, 0
	global_load_dword v12, v129, s[26:27]
	s_add_u32 s26, s22, 0x200000
	s_addc_u32 s27, s23, 0
	global_load_dword v13, v129, s[26:27]
	s_add_u32 s26, s22, 0x380000
	s_addc_u32 s27, s23, 0
	global_load_dword v14, v129, s[26:27]
	s_waitcnt vmcnt(43)
	v_max3_f32 v132, v28, v29, v30
	v_sub_f32_e32 v133, v28, v132
	v_sub_f32_e32 v134, v29, v132
	v_sub_f32_e32 v135, v30, v132
	v_mul_f32_e32 v133, 0x3fb8aa3b, v133
	v_mul_f32_e32 v134, 0x3fb8aa3b, v134
	v_mul_f32_e32 v135, 0x3fb8aa3b, v135
	v_exp_f32_e32 v133, v133
	v_exp_f32_e32 v134, v134
	v_exp_f32_e32 v135, v135
	s_nop 0
	v_add_f32_e32 v136, v133, v134
	v_add_f32_e32 v136, v135, v136
	v_div_scale_f32 v137, s[28:29], v136, v136, 1.0
	v_rcp_f32_e32 v138, v137
	v_div_scale_f32 v139, vcc, 1.0, v136, 1.0
	s_nop 0
	v_fma_f32 v140, -v137, v138, 1.0
	v_fmac_f32_e32 v138, v140, v138
	v_mul_f32_e32 v141, v139, v138
	v_fma_f32 v140, -v137, v141, v139
	v_fmac_f32_e32 v141, v140, v138
	v_fma_f32 v137, -v137, v141, v139
	v_div_fmas_f32 v137, v137, v138, v141
	v_div_fixup_f32 v136, v137, v136, 1.0
	v_mul_f32_e32 v133, v133, v136
	v_mul_f32_e32 v134, v134, v136
	v_mul_f32_e32 v135, v135, v136
	v_lshlrev_b32_e32 v142, 16, v16
	v_and_b32_e32 v145, 0xffff0000, v16
	v_lshlrev_b32_e32 v143, 16, v20
	v_and_b32_e32 v146, 0xffff0000, v20
	v_lshlrev_b32_e32 v144, 16, v24
	v_and_b32_e32 v147, 0xffff0000, v24
	v_mul_f32_e32 v148, v133, v142
	v_mul_f32_e32 v149, v133, v145
	v_fmac_f32_e32 v148, v134, v143
	v_fmac_f32_e32 v149, v134, v146
	v_fmac_f32_e32 v148, v135, v144
	v_fmac_f32_e32 v149, v135, v147
	v_cvt_pk_bf16_f32 v164, v148, v149
	v_lshlrev_b32_e32 v142, 16, v17
	v_and_b32_e32 v145, 0xffff0000, v17
	v_lshlrev_b32_e32 v143, 16, v21
	v_and_b32_e32 v146, 0xffff0000, v21
	v_lshlrev_b32_e32 v144, 16, v25
	v_and_b32_e32 v147, 0xffff0000, v25
	v_mul_f32_e32 v148, v133, v142
	v_mul_f32_e32 v149, v133, v145
	v_fmac_f32_e32 v148, v134, v143
	v_fmac_f32_e32 v149, v134, v146
	v_fmac_f32_e32 v148, v135, v144
	v_fmac_f32_e32 v149, v135, v147
	v_cvt_pk_bf16_f32 v165, v148, v149
	v_lshlrev_b32_e32 v142, 16, v18
	v_and_b32_e32 v145, 0xffff0000, v18
	v_lshlrev_b32_e32 v143, 16, v22
	v_and_b32_e32 v146, 0xffff0000, v22
	v_lshlrev_b32_e32 v144, 16, v26
	v_and_b32_e32 v147, 0xffff0000, v26
	v_mul_f32_e32 v148, v133, v142
	v_mul_f32_e32 v149, v133, v145
	v_fmac_f32_e32 v148, v134, v143
	v_fmac_f32_e32 v149, v134, v146
	v_fmac_f32_e32 v148, v135, v144
	v_fmac_f32_e32 v149, v135, v147
	v_cvt_pk_bf16_f32 v166, v148, v149
	v_lshlrev_b32_e32 v142, 16, v19
	v_and_b32_e32 v145, 0xffff0000, v19
	v_lshlrev_b32_e32 v143, 16, v23
	v_and_b32_e32 v146, 0xffff0000, v23
	v_lshlrev_b32_e32 v144, 16, v27
	v_and_b32_e32 v147, 0xffff0000, v27
	v_mul_f32_e32 v148, v133, v142
	v_mul_f32_e32 v149, v133, v145
	v_fmac_f32_e32 v148, v134, v143
	v_fmac_f32_e32 v149, v134, v146
	v_fmac_f32_e32 v148, v135, v144
	v_fmac_f32_e32 v149, v135, v147
	v_cvt_pk_bf16_f32 v167, v148, v149
	s_add_u32 s26, s24, 0x200000
	s_addc_u32 s27, s25, 0
	global_store_dwordx4 v128, v[164:167], s[26:27]
	s_add_u32 s26, s20, 0x1200000
	s_addc_u32 s27, s21, 0
	global_load_dwordx4 v[16:19], v128, s[26:27]
	s_add_u32 s26, s20, 0x4200000
	s_addc_u32 s27, s21, 0
	global_load_dwordx4 v[20:23], v128, s[26:27]
	s_add_u32 s26, s20, 0x7200000
	s_addc_u32 s27, s21, 0
	global_load_dwordx4 v[24:27], v128, s[26:27]
	s_add_u32 s26, s22, 0x90000
	s_addc_u32 s27, s23, 0
	global_load_dword v28, v129, s[26:27]
	s_add_u32 s26, s22, 0x210000
	s_addc_u32 s27, s23, 0
	global_load_dword v29, v129, s[26:27]
	s_add_u32 s26, s22, 0x390000
	s_addc_u32 s27, s23, 0
	global_load_dword v30, v129, s[26:27]
	s_waitcnt vmcnt(44)
; __device__ __forceinline__ float bf_lo(unsigned w) { return __uint_as_float(w << 16); }
; __device__ __forceinline__ float bf_hi(unsigned w) { return __uint_as_float(w & 0xffff0000u); }
; __device__ __forceinline__ unsigned pk2(float lo, float hi) { return pg8::cvt_pk_bf16(lo, hi); }
; __device__ __forceinline__ void merge_rows(const Args& a, int gw, int NGW, int lane) {
;     ...
;         for (int r = 0; r < 4; ++r) { const int m = mb + r * NGW; const int mc = m < MT ? m : mb;
; #pragma unroll
;             for (int g = 0; g < 3; ++g) { l[r][g] = LSE[((size_t)g * MT + mc) * 4 + hh]; o[r][g] = *(const v2u*)(OG + ((size_t)g * MT + mc) * 256 + 4 * lane); } }
;     ...
;         for (int r = 0; r < 4; ++r) { const int m = mb + r * NGW; if (m < MT) {
;             const float mxl = fmaxf(l[r][0], fmaxf(l[r][1], l[r][2]));
;             float a0 = __expf(l[r][0] - mxl), a1 = __expf(l[r][1] - mxl), a2 = __expf(l[r][2] - mxl); const float is = 1.0f / (a0 + a1 + a2); a0 *= is; a1 *= is; a2 *= is;
;             const v2u o0 = o[r][0], o1 = o[r][1], o2 = o[r][2];
;             v2u w;
;             w.x = pk2(a0 * pg8::bf_lo(o0.x) + a1 * pg8::bf_lo(o1.x) + a2 * pg8::bf_lo(o2.x), a0 * pg8::bf_hi(o0.x) + a1 * pg8::bf_hi(o1.x) + a2 * pg8::bf_hi(o2.x));
;             w.y = pk2(a0 * pg8::bf_lo(o0.y) + a1 * pg8::bf_lo(o1.y) + a2 * pg8::bf_lo(o2.y), a0 * pg8::bf_hi(o0.y) + a1 * pg8::bf_hi(o1.y) + a2 * pg8::bf_hi(o2.y));
;             *(v2u*)(YAT + (size_t)m * 256 + 4 * lane) = w; } }
	v_max3_f32 v132, v44, v45, v46
	v_sub_f32_e32 v133, v44, v132
	v_sub_f32_e32 v134, v45, v132
	v_sub_f32_e32 v135, v46, v132
	v_mul_f32_e32 v133, 0x3fb8aa3b, v133
	v_mul_f32_e32 v134, 0x3fb8aa3b, v134
	v_mul_f32_e32 v135, 0x3fb8aa3b, v135
	v_exp_f32_e32 v133, v133
	v_exp_f32_e32 v134, v134
	v_exp_f32_e32 v135, v135
	s_nop 0
	v_add_f32_e32 v136, v133, v134
	v_add_f32_e32 v136, v135, v136
	v_div_scale_f32 v137, s[28:29], v136, v136, 1.0
	v_rcp_f32_e32 v138, v137
	v_div_scale_f32 v139, vcc, 1.0, v136, 1.0
	s_nop 0
	v_fma_f32 v140, -v137, v138, 1.0
	v_fmac_f32_e32 v138, v140, v138
	v_mul_f32_e32 v141, v139, v138
	v_fma_f32 v140, -v137, v141, v139
	v_fmac_f32_e32 v141, v140, v138
	v_fma_f32 v137, -v137, v141, v139
	v_div_fmas_f32 v137, v137, v138, v141
	v_div_fixup_f32 v136, v137, v136, 1.0
	v_mul_f32_e32 v133, v133, v136
	v_mul_f32_e32 v134, v134, v136
	v_mul_f32_e32 v135, v135, v136
	v_lshlrev_b32_e32 v142, 16, v32
	v_and_b32_e32 v145, 0xffff0000, v32
	v_lshlrev_b32_e32 v143, 16, v36
	v_and_b32_e32 v146, 0xffff0000, v36
	v_lshlrev_b32_e32 v144, 16, v40
	v_and_b32_e32 v147, 0xffff0000, v40
	v_mul_f32_e32 v148, v133, v142
	v_mul_f32_e32 v149, v133, v145
	v_fmac_f32_e32 v148, v134, v143
	v_fmac_f32_e32 v149, v134, v146
	v_fmac_f32_e32 v148, v135, v144
	v_fmac_f32_e32 v149, v135, v147
	v_cvt_pk_bf16_f32 v160, v148, v149
	v_lshlrev_b32_e32 v142, 16, v33
	v_and_b32_e32 v145, 0xffff0000, v33
	v_lshlrev_b32_e32 v143, 16, v37
	v_and_b32_e32 v146, 0xffff0000, v37
	v_lshlrev_b32_e32 v144, 16, v41
	v_and_b32_e32 v147, 0xffff0000, v41
	v_mul_f32_e32 v148, v133, v142
	v_mul_f32_e32 v149, v133, v145
	v_fmac_f32_e32 v148, v134, v143
	v_fmac_f32_e32 v149, v134, v146
	v_fmac_f32_e32 v148, v135, v144
	v_fmac_f32_e32 v149, v135, v147
	v_cvt_pk_bf16_f32 v161, v148, v149
	v_lshlrev_b32_e32 v142, 16, v34
	v_and_b32_e32 v145, 0xffff0000, v34
	v_lshlrev_b32_e32 v143, 16, v38
	v_and_b32_e32 v146, 0xffff0000, v38
	v_lshlrev_b32_e32 v144, 16, v42
	v_and_b32_e32 v147, 0xffff0000, v42
	v_mul_f32_e32 v148, v133, v142
	v_mul_f32_e32 v149, v133, v145
	v_fmac_f32_e32 v148, v134, v143
	v_fmac_f32_e32 v149, v134, v146
	v_fmac_f32_e32 v148, v135, v144
	v_fmac_f32_e32 v149, v135, v147
	v_cvt_pk_bf16_f32 v162, v148, v149
	v_lshlrev_b32_e32 v142, 16, v35
	v_and_b32_e32 v145, 0xffff0000, v35
	v_lshlrev_b32_e32 v143, 16, v39
	v_and_b32_e32 v146, 0xffff0000, v39
	v_lshlrev_b32_e32 v144, 16, v43
	v_and_b32_e32 v147, 0xffff0000, v43
	v_mul_f32_e32 v148, v133, v142
	v_mul_f32_e32 v149, v133, v145
	v_fmac_f32_e32 v148, v134, v143
	v_fmac_f32_e32 v149, v134, v146
	v_fmac_f32_e32 v148, v135, v144
	v_fmac_f32_e32 v149, v135, v147
	v_cvt_pk_bf16_f32 v163, v148, v149
	s_add_u32 s26, s24, 0x400000
	s_addc_u32 s27, s25, 0
	global_store_dwordx4 v128, v[160:163], s[26:27]
	s_add_u32 s26, s20, 0x1400000
	s_addc_u32 s27, s21, 0
	global_load_dwordx4 v[32:35], v128, s[26:27]
	s_add_u32 s26, s20, 0x4400000
	s_addc_u32 s27, s21, 0
	global_load_dwordx4 v[36:39], v128, s[26:27]
	s_add_u32 s26, s20, 0x7400000
	s_addc_u32 s27, s21, 0
	global_load_dwordx4 v[40:43], v128, s[26:27]
	s_add_u32 s26, s22, 0xa0000
	s_addc_u32 s27, s23, 0
	global_load_dword v44, v129, s[26:27]
	s_add_u32 s26, s22, 0x220000
	s_addc_u32 s27, s23, 0
	global_load_dword v45, v129, s[26:27]
	s_add_u32 s26, s22, 0x3a0000
	s_addc_u32 s27, s23, 0
	global_load_dword v46, v129, s[26:27]
	s_waitcnt vmcnt(45)
	v_max3_f32 v132, v60, v61, v62
	v_sub_f32_e32 v133, v60, v132
	v_sub_f32_e32 v134, v61, v132
	v_sub_f32_e32 v135, v62, v132
	v_mul_f32_e32 v133, 0x3fb8aa3b, v133
	v_mul_f32_e32 v134, 0x3fb8aa3b, v134
	v_mul_f32_e32 v135, 0x3fb8aa3b, v135
	v_exp_f32_e32 v133, v133
	v_exp_f32_e32 v134, v134
	v_exp_f32_e32 v135, v135
	s_nop 0
	v_add_f32_e32 v136, v133, v134
	v_add_f32_e32 v136, v135, v136
	v_div_scale_f32 v137, s[28:29], v136, v136, 1.0
	v_rcp_f32_e32 v138, v137
	v_div_scale_f32 v139, vcc, 1.0, v136, 1.0
	s_nop 0
	v_fma_f32 v140, -v137, v138, 1.0
	v_fmac_f32_e32 v138, v140, v138
	v_mul_f32_e32 v141, v139, v138
	v_fma_f32 v140, -v137, v141, v139
	v_fmac_f32_e32 v141, v140, v138
	v_fma_f32 v137, -v137, v141, v139
	v_div_fmas_f32 v137, v137, v138, v141
	v_div_fixup_f32 v136, v137, v136, 1.0
	v_mul_f32_e32 v133, v133, v136
	v_mul_f32_e32 v134, v134, v136
	v_mul_f32_e32 v135, v135, v136
	v_lshlrev_b32_e32 v142, 16, v48
	v_and_b32_e32 v145, 0xffff0000, v48
	v_lshlrev_b32_e32 v143, 16, v52
	v_and_b32_e32 v146, 0xffff0000, v52
	v_lshlrev_b32_e32 v144, 16, v56
	v_and_b32_e32 v147, 0xffff0000, v56
	v_mul_f32_e32 v148, v133, v142
	v_mul_f32_e32 v149, v133, v145
	v_fmac_f32_e32 v148, v134, v143
	v_fmac_f32_e32 v149, v134, v146
	v_fmac_f32_e32 v148, v135, v144
	v_fmac_f32_e32 v149, v135, v147
	v_cvt_pk_bf16_f32 v164, v148, v149
	v_lshlrev_b32_e32 v142, 16, v49
	v_and_b32_e32 v145, 0xffff0000, v49
	v_lshlrev_b32_e32 v143, 16, v53
	v_and_b32_e32 v146, 0xffff0000, v53
	v_lshlrev_b32_e32 v144, 16, v57
	v_and_b32_e32 v147, 0xffff0000, v57
	v_mul_f32_e32 v148, v133, v142
	v_mul_f32_e32 v149, v133, v145
	v_fmac_f32_e32 v148, v134, v143
	v_fmac_f32_e32 v149, v134, v146
	v_fmac_f32_e32 v148, v135, v144
	v_fmac_f32_e32 v149, v135, v147
	v_cvt_pk_bf16_f32 v165, v148, v149
	v_lshlrev_b32_e32 v142, 16, v50
	v_and_b32_e32 v145, 0xffff0000, v50
	v_lshlrev_b32_e32 v143, 16, v54
	v_and_b32_e32 v146, 0xffff0000, v54
	v_lshlrev_b32_e32 v144, 16, v58
	v_and_b32_e32 v147, 0xffff0000, v58
	v_mul_f32_e32 v148, v133, v142
	v_mul_f32_e32 v149, v133, v145
	v_fmac_f32_e32 v148, v134, v143
	v_fmac_f32_e32 v149, v134, v146
	v_fmac_f32_e32 v148, v135, v144
	v_fmac_f32_e32 v149, v135, v147
	v_cvt_pk_bf16_f32 v166, v148, v149
	v_lshlrev_b32_e32 v142, 16, v51
	v_and_b32_e32 v145, 0xffff0000, v51
	v_lshlrev_b32_e32 v143, 16, v55
	v_and_b32_e32 v146, 0xffff0000, v55
	v_lshlrev_b32_e32 v144, 16, v59
	v_and_b32_e32 v147, 0xffff0000, v59
	v_mul_f32_e32 v148, v133, v142
	v_mul_f32_e32 v149, v133, v145
	v_fmac_f32_e32 v148, v134, v143
	v_fmac_f32_e32 v149, v134, v146
	v_fmac_f32_e32 v148, v135, v144
	v_fmac_f32_e32 v149, v135, v147
	v_cvt_pk_bf16_f32 v167, v148, v149
	s_add_u32 s26, s24, 0x600000
	s_addc_u32 s27, s25, 0
	global_store_dwordx4 v128, v[164:167], s[26:27]
	s_add_u32 s26, s20, 0x1600000
	s_addc_u32 s27, s21, 0
	global_load_dwordx4 v[48:51], v128, s[26:27]
	s_add_u32 s26, s20, 0x4600000
	s_addc_u32 s27, s21, 0
	global_load_dwordx4 v[52:55], v128, s[26:27]
	s_add_u32 s26, s20, 0x7600000
	s_addc_u32 s27, s21, 0
	global_load_dwordx4 v[56:59], v128, s[26:27]
	s_add_u32 s26, s22, 0xb0000
	s_addc_u32 s27, s23, 0
	global_load_dword v60, v129, s[26:27]
	s_add_u32 s26, s22, 0x230000
	s_addc_u32 s27, s23, 0
	global_load_dword v61, v129, s[26:27]
	s_add_u32 s26, s22, 0x3b0000
	s_addc_u32 s27, s23, 0
	global_load_dword v62, v129, s[26:27]
	s_waitcnt vmcnt(46)
; __device__ __forceinline__ float bf_lo(unsigned w) { return __uint_as_float(w << 16); }
; __device__ __forceinline__ float bf_hi(unsigned w) { return __uint_as_float(w & 0xffff0000u); }
; __device__ __forceinline__ unsigned pk2(float lo, float hi) { return pg8::cvt_pk_bf16(lo, hi); }
; __device__ __forceinline__ void merge_rows(const Args& a, int gw, int NGW, int lane) {
;     ...
;         for (int r = 0; r < 4; ++r) { const int m = mb + r * NGW; const int mc = m < MT ? m : mb;
; #pragma unroll
;             for (int g = 0; g < 3; ++g) { l[r][g] = LSE[((size_t)g * MT + mc) * 4 + hh]; o[r][g] = *(const v2u*)(OG + ((size_t)g * MT + mc) * 256 + 4 * lane); } }
;     ...
;         for (int r = 0; r < 4; ++r) { const int m = mb + r * NGW; if (m < MT) {
;             const float mxl = fmaxf(l[r][0], fmaxf(l[r][1], l[r][2]));
;             float a0 = __expf(l[r][0] - mxl), a1 = __expf(l[r][1] - mxl), a2 = __expf(l[r][2] - mxl); const float is = 1.0f / (a0 + a1 + a2); a0 *= is; a1 *= is; a2 *= is;
;             const v2u o0 = o[r][0], o1 = o[r][1], o2 = o[r][2];
;             v2u w;
;             w.x = pk2(a0 * pg8::bf_lo(o0.x) + a1 * pg8::bf_lo(o1.x) + a2 * pg8::bf_lo(o2.x), a0 * pg8::bf_hi(o0.x) + a1 * pg8::bf_hi(o1.x) + a2 * pg8::bf_hi(o2.x));
;             w.y = pk2(a0 * pg8::bf_lo(o0.y) + a1 * pg8::bf_lo(o1.y) + a2 * pg8::bf_lo(o2.y), a0 * pg8::bf_hi(o0.y) + a1 * pg8::bf_hi(o1.y) + a2 * pg8::bf_hi(o2.y));
;             *(v2u*)(YAT + (size_t)m * 256 + 4 * lane) = w; } }
	v_max3_f32 v132, v76, v77, v78
	v_sub_f32_e32 v133, v76, v132
	v_sub_f32_e32 v134, v77, v132
	v_sub_f32_e32 v135, v78, v132
	v_mul_f32_e32 v133, 0x3fb8aa3b, v133
	v_mul_f32_e32 v134, 0x3fb8aa3b, v134
	v_mul_f32_e32 v135, 0x3fb8aa3b, v135
	v_exp_f32_e32 v133, v133
	v_exp_f32_e32 v134, v134
	v_exp_f32_e32 v135, v135
	s_nop 0
	v_add_f32_e32 v136, v133, v134
	v_add_f32_e32 v136, v135, v136
	v_div_scale_f32 v137, s[28:29], v136, v136, 1.0
	v_rcp_f32_e32 v138, v137
	v_div_scale_f32 v139, vcc, 1.0, v136, 1.0
	s_nop 0
	v_fma_f32 v140, -v137, v138, 1.0
	v_fmac_f32_e32 v138, v140, v138
	v_mul_f32_e32 v141, v139, v138
	v_fma_f32 v140, -v137, v141, v139
	v_fmac_f32_e32 v141, v140, v138
	v_fma_f32 v137, -v137, v141, v139
	v_div_fmas_f32 v137, v137, v138, v141
	v_div_fixup_f32 v136, v137, v136, 1.0
	v_mul_f32_e32 v133, v133, v136
	v_mul_f32_e32 v134, v134, v136
	v_mul_f32_e32 v135, v135, v136
	v_lshlrev_b32_e32 v142, 16, v64
	v_and_b32_e32 v145, 0xffff0000, v64
	v_lshlrev_b32_e32 v143, 16, v68
	v_and_b32_e32 v146, 0xffff0000, v68
	v_lshlrev_b32_e32 v144, 16, v72
	v_and_b32_e32 v147, 0xffff0000, v72
	v_mul_f32_e32 v148, v133, v142
	v_mul_f32_e32 v149, v133, v145
	v_fmac_f32_e32 v148, v134, v143
	v_fmac_f32_e32 v149, v134, v146
	v_fmac_f32_e32 v148, v135, v144
	v_fmac_f32_e32 v149, v135, v147
	v_cvt_pk_bf16_f32 v160, v148, v149
	v_lshlrev_b32_e32 v142, 16, v65
	v_and_b32_e32 v145, 0xffff0000, v65
	v_lshlrev_b32_e32 v143, 16, v69
	v_and_b32_e32 v146, 0xffff0000, v69
	v_lshlrev_b32_e32 v144, 16, v73
	v_and_b32_e32 v147, 0xffff0000, v73
	v_mul_f32_e32 v148, v133, v142
	v_mul_f32_e32 v149, v133, v145
	v_fmac_f32_e32 v148, v134, v143
	v_fmac_f32_e32 v149, v134, v146
	v_fmac_f32_e32 v148, v135, v144
	v_fmac_f32_e32 v149, v135, v147
	v_cvt_pk_bf16_f32 v161, v148, v149
	v_lshlrev_b32_e32 v142, 16, v66
	v_and_b32_e32 v145, 0xffff0000, v66
	v_lshlrev_b32_e32 v143, 16, v70
	v_and_b32_e32 v146, 0xffff0000, v70
	v_lshlrev_b32_e32 v144, 16, v74
	v_and_b32_e32 v147, 0xffff0000, v74
	v_mul_f32_e32 v148, v133, v142
	v_mul_f32_e32 v149, v133, v145
	v_fmac_f32_e32 v148, v134, v143
	v_fmac_f32_e32 v149, v134, v146
	v_fmac_f32_e32 v148, v135, v144
	v_fmac_f32_e32 v149, v135, v147
	v_cvt_pk_bf16_f32 v162, v148, v149
	v_lshlrev_b32_e32 v142, 16, v67
	v_and_b32_e32 v145, 0xffff0000, v67
	v_lshlrev_b32_e32 v143, 16, v71
	v_and_b32_e32 v146, 0xffff0000, v71
	v_lshlrev_b32_e32 v144, 16, v75
	v_and_b32_e32 v147, 0xffff0000, v75
	v_mul_f32_e32 v148, v133, v142
	v_mul_f32_e32 v149, v133, v145
	v_fmac_f32_e32 v148, v134, v143
	v_fmac_f32_e32 v149, v134, v146
	v_fmac_f32_e32 v148, v135, v144
	v_fmac_f32_e32 v149, v135, v147
	v_cvt_pk_bf16_f32 v163, v148, v149
	s_add_u32 s26, s24, 0x800000
	s_addc_u32 s27, s25, 0
	global_store_dwordx4 v128, v[160:163], s[26:27]
	s_add_u32 s26, s20, 0x1800000
	s_addc_u32 s27, s21, 0
	global_load_dwordx4 v[64:67], v128, s[26:27]
	s_add_u32 s26, s20, 0x4800000
	s_addc_u32 s27, s21, 0
	global_load_dwordx4 v[68:71], v128, s[26:27]
	s_add_u32 s26, s20, 0x7800000
	s_addc_u32 s27, s21, 0
	global_load_dwordx4 v[72:75], v128, s[26:27]
	s_add_u32 s26, s22, 0xc0000
	s_addc_u32 s27, s23, 0
	global_load_dword v76, v129, s[26:27]
	s_add_u32 s26, s22, 0x240000
	s_addc_u32 s27, s23, 0
	global_load_dword v77, v129, s[26:27]
	s_add_u32 s26, s22, 0x3c0000
	s_addc_u32 s27, s23, 0
	global_load_dword v78, v129, s[26:27]
	s_waitcnt vmcnt(47)
	v_max3_f32 v132, v92, v93, v94
	v_sub_f32_e32 v133, v92, v132
	v_sub_f32_e32 v134, v93, v132
	v_sub_f32_e32 v135, v94, v132
	v_mul_f32_e32 v133, 0x3fb8aa3b, v133
	v_mul_f32_e32 v134, 0x3fb8aa3b, v134
	v_mul_f32_e32 v135, 0x3fb8aa3b, v135
	v_exp_f32_e32 v133, v133
	v_exp_f32_e32 v134, v134
	v_exp_f32_e32 v135, v135
	s_nop 0
	v_add_f32_e32 v136, v133, v134
	v_add_f32_e32 v136, v135, v136
	v_div_scale_f32 v137, s[28:29], v136, v136, 1.0
	v_rcp_f32_e32 v138, v137
	v_div_scale_f32 v139, vcc, 1.0, v136, 1.0
	s_nop 0
	v_fma_f32 v140, -v137, v138, 1.0
	v_fmac_f32_e32 v138, v140, v138
	v_mul_f32_e32 v141, v139, v138
	v_fma_f32 v140, -v137, v141, v139
	v_fmac_f32_e32 v141, v140, v138
	v_fma_f32 v137, -v137, v141, v139
	v_div_fmas_f32 v137, v137, v138, v141
	v_div_fixup_f32 v136, v137, v136, 1.0
	v_mul_f32_e32 v133, v133, v136
	v_mul_f32_e32 v134, v134, v136
	v_mul_f32_e32 v135, v135, v136
	v_lshlrev_b32_e32 v142, 16, v80
	v_and_b32_e32 v145, 0xffff0000, v80
	v_lshlrev_b32_e32 v143, 16, v84
	v_and_b32_e32 v146, 0xffff0000, v84
	v_lshlrev_b32_e32 v144, 16, v88
	v_and_b32_e32 v147, 0xffff0000, v88
	v_mul_f32_e32 v148, v133, v142
	v_mul_f32_e32 v149, v133, v145
	v_fmac_f32_e32 v148, v134, v143
	v_fmac_f32_e32 v149, v134, v146
	v_fmac_f32_e32 v148, v135, v144
	v_fmac_f32_e32 v149, v135, v147
	v_cvt_pk_bf16_f32 v164, v148, v149
	v_lshlrev_b32_e32 v142, 16, v81
	v_and_b32_e32 v145, 0xffff0000, v81
	v_lshlrev_b32_e32 v143, 16, v85
	v_and_b32_e32 v146, 0xffff0000, v85
	v_lshlrev_b32_e32 v144, 16, v89
	v_and_b32_e32 v147, 0xffff0000, v89
	v_mul_f32_e32 v148, v133, v142
	v_mul_f32_e32 v149, v133, v145
	v_fmac_f32_e32 v148, v134, v143
	v_fmac_f32_e32 v149, v134, v146
	v_fmac_f32_e32 v148, v135, v144
	v_fmac_f32_e32 v149, v135, v147
	v_cvt_pk_bf16_f32 v165, v148, v149
	v_lshlrev_b32_e32 v142, 16, v82
	v_and_b32_e32 v145, 0xffff0000, v82
	v_lshlrev_b32_e32 v143, 16, v86
	v_and_b32_e32 v146, 0xffff0000, v86
	v_lshlrev_b32_e32 v144, 16, v90
	v_and_b32_e32 v147, 0xffff0000, v90
	v_mul_f32_e32 v148, v133, v142
	v_mul_f32_e32 v149, v133, v145
	v_fmac_f32_e32 v148, v134, v143
	v_fmac_f32_e32 v149, v134, v146
	v_fmac_f32_e32 v148, v135, v144
	v_fmac_f32_e32 v149, v135, v147
	v_cvt_pk_bf16_f32 v166, v148, v149
	v_lshlrev_b32_e32 v142, 16, v83
	v_and_b32_e32 v145, 0xffff0000, v83
	v_lshlrev_b32_e32 v143, 16, v87
	v_and_b32_e32 v146, 0xffff0000, v87
	v_lshlrev_b32_e32 v144, 16, v91
	v_and_b32_e32 v147, 0xffff0000, v91
	v_mul_f32_e32 v148, v133, v142
	v_mul_f32_e32 v149, v133, v145
	v_fmac_f32_e32 v148, v134, v143
	v_fmac_f32_e32 v149, v134, v146
	v_fmac_f32_e32 v148, v135, v144
	v_fmac_f32_e32 v149, v135, v147
	v_cvt_pk_bf16_f32 v167, v148, v149
	s_add_u32 s26, s24, 0xa00000
	s_addc_u32 s27, s25, 0
	global_store_dwordx4 v128, v[164:167], s[26:27]
	s_add_u32 s26, s20, 0x1a00000
	s_addc_u32 s27, s21, 0
	global_load_dwordx4 v[80:83], v128, s[26:27]
	s_add_u32 s26, s20, 0x4a00000
	s_addc_u32 s27, s21, 0
	global_load_dwordx4 v[84:87], v128, s[26:27]
	s_add_u32 s26, s20, 0x7a00000
	s_addc_u32 s27, s21, 0
	global_load_dwordx4 v[88:91], v128, s[26:27]
	s_add_u32 s26, s22, 0xd0000
	s_addc_u32 s27, s23, 0
	global_load_dword v92, v129, s[26:27]
	s_add_u32 s26, s22, 0x250000
	s_addc_u32 s27, s23, 0
	global_load_dword v93, v129, s[26:27]
	s_add_u32 s26, s22, 0x3d0000
	s_addc_u32 s27, s23, 0
	global_load_dword v94, v129, s[26:27]
	s_waitcnt vmcnt(48)
; __device__ __forceinline__ float bf_lo(unsigned w) { return __uint_as_float(w << 16); }
; __device__ __forceinline__ float bf_hi(unsigned w) { return __uint_as_float(w & 0xffff0000u); }
; __device__ __forceinline__ unsigned pk2(float lo, float hi) { return pg8::cvt_pk_bf16(lo, hi); }
; __device__ __forceinline__ void merge_rows(const Args& a, int gw, int NGW, int lane) {
;     ...
;         for (int r = 0; r < 4; ++r) { const int m = mb + r * NGW; const int mc = m < MT ? m : mb;
; #pragma unroll
;             for (int g = 0; g < 3; ++g) { l[r][g] = LSE[((size_t)g * MT + mc) * 4 + hh]; o[r][g] = *(const v2u*)(OG + ((size_t)g * MT + mc) * 256 + 4 * lane); } }
;     ...
;         for (int r = 0; r < 4; ++r) { const int m = mb + r * NGW; if (m < MT) {
;             const float mxl = fmaxf(l[r][0], fmaxf(l[r][1], l[r][2]));
;             float a0 = __expf(l[r][0] - mxl), a1 = __expf(l[r][1] - mxl), a2 = __expf(l[r][2] - mxl); const float is = 1.0f / (a0 + a1 + a2); a0 *= is; a1 *= is; a2 *= is;
;             const v2u o0 = o[r][0], o1 = o[r][1], o2 = o[r][2];
;             v2u w;
;             w.x = pk2(a0 * pg8::bf_lo(o0.x) + a1 * pg8::bf_lo(o1.x) + a2 * pg8::bf_lo(o2.x), a0 * pg8::bf_hi(o0.x) + a1 * pg8::bf_hi(o1.x) + a2 * pg8::bf_hi(o2.x));
;             w.y = pk2(a0 * pg8::bf_lo(o0.y) + a1 * pg8::bf_lo(o1.y) + a2 * pg8::bf_lo(o2.y), a0 * pg8::bf_hi(o0.y) + a1 * pg8::bf_hi(o1.y) + a2 * pg8::bf_hi(o2.y));
;             *(v2u*)(YAT + (size_t)m * 256 + 4 * lane) = w; } }
	v_max3_f32 v132, v108, v109, v110
	v_sub_f32_e32 v133, v108, v132
	v_sub_f32_e32 v134, v109, v132
	v_sub_f32_e32 v135, v110, v132
	v_mul_f32_e32 v133, 0x3fb8aa3b, v133
	v_mul_f32_e32 v134, 0x3fb8aa3b, v134
	v_mul_f32_e32 v135, 0x3fb8aa3b, v135
	v_exp_f32_e32 v133, v133
	v_exp_f32_e32 v134, v134
	v_exp_f32_e32 v135, v135
	s_nop 0
	v_add_f32_e32 v136, v133, v134
	v_add_f32_e32 v136, v135, v136
	v_div_scale_f32 v137, s[28:29], v136, v136, 1.0
	v_rcp_f32_e32 v138, v137
	v_div_scale_f32 v139, vcc, 1.0, v136, 1.0
	s_nop 0
	v_fma_f32 v140, -v137, v138, 1.0
	v_fmac_f32_e32 v138, v140, v138
	v_mul_f32_e32 v141, v139, v138
	v_fma_f32 v140, -v137, v141, v139
	v_fmac_f32_e32 v141, v140, v138
	v_fma_f32 v137, -v137, v141, v139
	v_div_fmas_f32 v137, v137, v138, v141
	v_div_fixup_f32 v136, v137, v136, 1.0
	v_mul_f32_e32 v133, v133, v136
	v_mul_f32_e32 v134, v134, v136
	v_mul_f32_e32 v135, v135, v136
	v_lshlrev_b32_e32 v142, 16, v96
	v_and_b32_e32 v145, 0xffff0000, v96
	v_lshlrev_b32_e32 v143, 16, v100
	v_and_b32_e32 v146, 0xffff0000, v100
	v_lshlrev_b32_e32 v144, 16, v104
	v_and_b32_e32 v147, 0xffff0000, v104
	v_mul_f32_e32 v148, v133, v142
	v_mul_f32_e32 v149, v133, v145
	v_fmac_f32_e32 v148, v134, v143
	v_fmac_f32_e32 v149, v134, v146
	v_fmac_f32_e32 v148, v135, v144
	v_fmac_f32_e32 v149, v135, v147
	v_cvt_pk_bf16_f32 v160, v148, v149
	v_lshlrev_b32_e32 v142, 16, v97
	v_and_b32_e32 v145, 0xffff0000, v97
	v_lshlrev_b32_e32 v143, 16, v101
	v_and_b32_e32 v146, 0xffff0000, v101
	v_lshlrev_b32_e32 v144, 16, v105
	v_and_b32_e32 v147, 0xffff0000, v105
	v_mul_f32_e32 v148, v133, v142
	v_mul_f32_e32 v149, v133, v145
	v_fmac_f32_e32 v148, v134, v143
	v_fmac_f32_e32 v149, v134, v146
	v_fmac_f32_e32 v148, v135, v144
	v_fmac_f32_e32 v149, v135, v147
	v_cvt_pk_bf16_f32 v161, v148, v149
	v_lshlrev_b32_e32 v142, 16, v98
	v_and_b32_e32 v145, 0xffff0000, v98
	v_lshlrev_b32_e32 v143, 16, v102
	v_and_b32_e32 v146, 0xffff0000, v102
	v_lshlrev_b32_e32 v144, 16, v106
	v_and_b32_e32 v147, 0xffff0000, v106
	v_mul_f32_e32 v148, v133, v142
	v_mul_f32_e32 v149, v133, v145
	v_fmac_f32_e32 v148, v134, v143
	v_fmac_f32_e32 v149, v134, v146
	v_fmac_f32_e32 v148, v135, v144
	v_fmac_f32_e32 v149, v135, v147
	v_cvt_pk_bf16_f32 v162, v148, v149
	v_lshlrev_b32_e32 v142, 16, v99
	v_and_b32_e32 v145, 0xffff0000, v99
	v_lshlrev_b32_e32 v143, 16, v103
	v_and_b32_e32 v146, 0xffff0000, v103
	v_lshlrev_b32_e32 v144, 16, v107
	v_and_b32_e32 v147, 0xffff0000, v107
	v_mul_f32_e32 v148, v133, v142
	v_mul_f32_e32 v149, v133, v145
	v_fmac_f32_e32 v148, v134, v143
	v_fmac_f32_e32 v149, v134, v146
	v_fmac_f32_e32 v148, v135, v144
	v_fmac_f32_e32 v149, v135, v147
	v_cvt_pk_bf16_f32 v163, v148, v149
	s_add_u32 s26, s24, 0xc00000
	s_addc_u32 s27, s25, 0
	global_store_dwordx4 v128, v[160:163], s[26:27]
	s_add_u32 s26, s20, 0x1c00000
	s_addc_u32 s27, s21, 0
	global_load_dwordx4 v[96:99], v128, s[26:27]
	s_add_u32 s26, s20, 0x4c00000
	s_addc_u32 s27, s21, 0
	global_load_dwordx4 v[100:103], v128, s[26:27]
	s_add_u32 s26, s20, 0x7c00000
	s_addc_u32 s27, s21, 0
	global_load_dwordx4 v[104:107], v128, s[26:27]
	s_add_u32 s26, s22, 0xe0000
	s_addc_u32 s27, s23, 0
	global_load_dword v108, v129, s[26:27]
	s_add_u32 s26, s22, 0x260000
	s_addc_u32 s27, s23, 0
	global_load_dword v109, v129, s[26:27]
	s_add_u32 s26, s22, 0x3e0000
	s_addc_u32 s27, s23, 0
	global_load_dword v110, v129, s[26:27]
	s_waitcnt vmcnt(49)
	v_max3_f32 v132, v124, v125, v126
	v_sub_f32_e32 v133, v124, v132
	v_sub_f32_e32 v134, v125, v132
	v_sub_f32_e32 v135, v126, v132
	v_mul_f32_e32 v133, 0x3fb8aa3b, v133
	v_mul_f32_e32 v134, 0x3fb8aa3b, v134
	v_mul_f32_e32 v135, 0x3fb8aa3b, v135
	v_exp_f32_e32 v133, v133
	v_exp_f32_e32 v134, v134
	v_exp_f32_e32 v135, v135
	s_nop 0
	v_add_f32_e32 v136, v133, v134
	v_add_f32_e32 v136, v135, v136
	v_div_scale_f32 v137, s[28:29], v136, v136, 1.0
	v_rcp_f32_e32 v138, v137
	v_div_scale_f32 v139, vcc, 1.0, v136, 1.0
	s_nop 0
	v_fma_f32 v140, -v137, v138, 1.0
	v_fmac_f32_e32 v138, v140, v138
	v_mul_f32_e32 v141, v139, v138
	v_fma_f32 v140, -v137, v141, v139
	v_fmac_f32_e32 v141, v140, v138
	v_fma_f32 v137, -v137, v141, v139
	v_div_fmas_f32 v137, v137, v138, v141
	v_div_fixup_f32 v136, v137, v136, 1.0
	v_mul_f32_e32 v133, v133, v136
	v_mul_f32_e32 v134, v134, v136
	v_mul_f32_e32 v135, v135, v136
	v_lshlrev_b32_e32 v142, 16, v112
	v_and_b32_e32 v145, 0xffff0000, v112
	v_lshlrev_b32_e32 v143, 16, v116
	v_and_b32_e32 v146, 0xffff0000, v116
	v_lshlrev_b32_e32 v144, 16, v120
	v_and_b32_e32 v147, 0xffff0000, v120
	v_mul_f32_e32 v148, v133, v142
	v_mul_f32_e32 v149, v133, v145
	v_fmac_f32_e32 v148, v134, v143
	v_fmac_f32_e32 v149, v134, v146
	v_fmac_f32_e32 v148, v135, v144
	v_fmac_f32_e32 v149, v135, v147
	v_cvt_pk_bf16_f32 v164, v148, v149
	v_lshlrev_b32_e32 v142, 16, v113
	v_and_b32_e32 v145, 0xffff0000, v113
	v_lshlrev_b32_e32 v143, 16, v117
	v_and_b32_e32 v146, 0xffff0000, v117
	v_lshlrev_b32_e32 v144, 16, v121
	v_and_b32_e32 v147, 0xffff0000, v121
	v_mul_f32_e32 v148, v133, v142
	v_mul_f32_e32 v149, v133, v145
	v_fmac_f32_e32 v148, v134, v143
	v_fmac_f32_e32 v149, v134, v146
	v_fmac_f32_e32 v148, v135, v144
	v_fmac_f32_e32 v149, v135, v147
	v_cvt_pk_bf16_f32 v165, v148, v149
	v_lshlrev_b32_e32 v142, 16, v114
	v_and_b32_e32 v145, 0xffff0000, v114
	v_lshlrev_b32_e32 v143, 16, v118
	v_and_b32_e32 v146, 0xffff0000, v118
	v_lshlrev_b32_e32 v144, 16, v122
	v_and_b32_e32 v147, 0xffff0000, v122
	v_mul_f32_e32 v148, v133, v142
	v_mul_f32_e32 v149, v133, v145
	v_fmac_f32_e32 v148, v134, v143
	v_fmac_f32_e32 v149, v134, v146
	v_fmac_f32_e32 v148, v135, v144
	v_fmac_f32_e32 v149, v135, v147
	v_cvt_pk_bf16_f32 v166, v148, v149
	v_lshlrev_b32_e32 v142, 16, v115
	v_and_b32_e32 v145, 0xffff0000, v115
	v_lshlrev_b32_e32 v143, 16, v119
	v_and_b32_e32 v146, 0xffff0000, v119
	v_lshlrev_b32_e32 v144, 16, v123
	v_and_b32_e32 v147, 0xffff0000, v123
	v_mul_f32_e32 v148, v133, v142
	v_mul_f32_e32 v149, v133, v145
	v_fmac_f32_e32 v148, v134, v143
	v_fmac_f32_e32 v149, v134, v146
	v_fmac_f32_e32 v148, v135, v144
	v_fmac_f32_e32 v149, v135, v147
	v_cvt_pk_bf16_f32 v167, v148, v149
	s_add_u32 s26, s24, 0xe00000
	s_addc_u32 s27, s25, 0
	global_store_dwordx4 v128, v[164:167], s[26:27]
	s_add_u32 s26, s20, 0x1e00000
	s_addc_u32 s27, s21, 0
	global_load_dwordx4 v[112:115], v128, s[26:27]
	s_add_u32 s26, s20, 0x4e00000
	s_addc_u32 s27, s21, 0
	global_load_dwordx4 v[116:119], v128, s[26:27]
	s_add_u32 s26, s20, 0x7e00000
	s_addc_u32 s27, s21, 0
	global_load_dwordx4 v[120:123], v128, s[26:27]
	s_add_u32 s26, s22, 0xf0000
	s_addc_u32 s27, s23, 0
	global_load_dword v124, v129, s[26:27]
	s_add_u32 s26, s22, 0x270000
	s_addc_u32 s27, s23, 0
	global_load_dword v125, v129, s[26:27]
	s_add_u32 s26, s22, 0x3f0000
	s_addc_u32 s27, s23, 0
	global_load_dword v126, v129, s[26:27]
	s_waitcnt vmcnt(49)
; __device__ __forceinline__ float bf_lo(unsigned w) { return __uint_as_float(w << 16); }
; __device__ __forceinline__ float bf_hi(unsigned w) { return __uint_as_float(w & 0xffff0000u); }
; __device__ __forceinline__ unsigned pk2(float lo, float hi) { return pg8::cvt_pk_bf16(lo, hi); }
; __device__ __forceinline__ void merge_rows(const Args& a, int gw, int NGW, int lane) {
;     ...
;         for (int r = 0; r < 4; ++r) { const int m = mb + r * NGW; const int mc = m < MT ? m : mb;
; #pragma unroll
;             for (int g = 0; g < 3; ++g) { l[r][g] = LSE[((size_t)g * MT + mc) * 4 + hh]; o[r][g] = *(const v2u*)(OG + ((size_t)g * MT + mc) * 256 + 4 * lane); } }
;     ...
;         for (int r = 0; r < 4; ++r) { const int m = mb + r * NGW; if (m < MT) {
;             const float mxl = fmaxf(l[r][0], fmaxf(l[r][1], l[r][2]));
;             float a0 = __expf(l[r][0] - mxl), a1 = __expf(l[r][1] - mxl), a2 = __expf(l[r][2] - mxl); const float is = 1.0f / (a0 + a1 + a2); a0 *= is; a1 *= is; a2 *= is;
;             const v2u o0 = o[r][0], o1 = o[r][1], o2 = o[r][2];
;             v2u w;
;             w.x = pk2(a0 * pg8::bf_lo(o0.x) + a1 * pg8::bf_lo(o1.x) + a2 * pg8::bf_lo(o2.x), a0 * pg8::bf_hi(o0.x) + a1 * pg8::bf_hi(o1.x) + a2 * pg8::bf_hi(o2.x));
;             w.y = pk2(a0 * pg8::bf_lo(o0.y) + a1 * pg8::bf_lo(o1.y) + a2 * pg8::bf_lo(o2.y), a0 * pg8::bf_hi(o0.y) + a1 * pg8::bf_hi(o1.y) + a2 * pg8::bf_hi(o2.y));
;             *(v2u*)(YAT + (size_t)m * 256 + 4 * lane) = w; } }
	v_max3_f32 v132, v12, v13, v14
	v_sub_f32_e32 v133, v12, v132
	v_sub_f32_e32 v134, v13, v132
	v_sub_f32_e32 v135, v14, v132
	v_mul_f32_e32 v133, 0x3fb8aa3b, v133
	v_mul_f32_e32 v134, 0x3fb8aa3b, v134
	v_mul_f32_e32 v135, 0x3fb8aa3b, v135
	v_exp_f32_e32 v133, v133
	v_exp_f32_e32 v134, v134
	v_exp_f32_e32 v135, v135
	s_nop 0
	v_add_f32_e32 v136, v133, v134
	v_add_f32_e32 v136, v135, v136
	v_div_scale_f32 v137, s[28:29], v136, v136, 1.0
	v_rcp_f32_e32 v138, v137
	v_div_scale_f32 v139, vcc, 1.0, v136, 1.0
	s_nop 0
	v_fma_f32 v140, -v137, v138, 1.0
	v_fmac_f32_e32 v138, v140, v138
	v_mul_f32_e32 v141, v139, v138
	v_fma_f32 v140, -v137, v141, v139
	v_fmac_f32_e32 v141, v140, v138
	v_fma_f32 v137, -v137, v141, v139
	v_div_fmas_f32 v137, v137, v138, v141
	v_div_fixup_f32 v136, v137, v136, 1.0
	v_mul_f32_e32 v133, v133, v136
	v_mul_f32_e32 v134, v134, v136
	v_mul_f32_e32 v135, v135, v136
	v_lshlrev_b32_e32 v142, 16, v0
	v_and_b32_e32 v145, 0xffff0000, v0
	v_lshlrev_b32_e32 v143, 16, v4
	v_and_b32_e32 v146, 0xffff0000, v4
	v_lshlrev_b32_e32 v144, 16, v8
	v_and_b32_e32 v147, 0xffff0000, v8
	v_mul_f32_e32 v148, v133, v142
	v_mul_f32_e32 v149, v133, v145
	v_fmac_f32_e32 v148, v134, v143
	v_fmac_f32_e32 v149, v134, v146
	v_fmac_f32_e32 v148, v135, v144
	v_fmac_f32_e32 v149, v135, v147
	v_cvt_pk_bf16_f32 v160, v148, v149
	v_lshlrev_b32_e32 v142, 16, v1
	v_and_b32_e32 v145, 0xffff0000, v1
	v_lshlrev_b32_e32 v143, 16, v5
	v_and_b32_e32 v146, 0xffff0000, v5
	v_lshlrev_b32_e32 v144, 16, v9
	v_and_b32_e32 v147, 0xffff0000, v9
	v_mul_f32_e32 v148, v133, v142
	v_mul_f32_e32 v149, v133, v145
	v_fmac_f32_e32 v148, v134, v143
	v_fmac_f32_e32 v149, v134, v146
	v_fmac_f32_e32 v148, v135, v144
	v_fmac_f32_e32 v149, v135, v147
	v_cvt_pk_bf16_f32 v161, v148, v149
	v_lshlrev_b32_e32 v142, 16, v2
	v_and_b32_e32 v145, 0xffff0000, v2
	v_lshlrev_b32_e32 v143, 16, v6
	v_and_b32_e32 v146, 0xffff0000, v6
	v_lshlrev_b32_e32 v144, 16, v10
	v_and_b32_e32 v147, 0xffff0000, v10
	v_mul_f32_e32 v148, v133, v142
	v_mul_f32_e32 v149, v133, v145
	v_fmac_f32_e32 v148, v134, v143
	v_fmac_f32_e32 v149, v134, v146
	v_fmac_f32_e32 v148, v135, v144
	v_fmac_f32_e32 v149, v135, v147
	v_cvt_pk_bf16_f32 v162, v148, v149
	v_lshlrev_b32_e32 v142, 16, v3
	v_and_b32_e32 v145, 0xffff0000, v3
	v_lshlrev_b32_e32 v143, 16, v7
	v_and_b32_e32 v146, 0xffff0000, v7
	v_lshlrev_b32_e32 v144, 16, v11
	v_and_b32_e32 v147, 0xffff0000, v11
	v_mul_f32_e32 v148, v133, v142
	v_mul_f32_e32 v149, v133, v145
	v_fmac_f32_e32 v148, v134, v143
	v_fmac_f32_e32 v149, v134, v146
	v_fmac_f32_e32 v148, v135, v144
	v_fmac_f32_e32 v149, v135, v147
	v_cvt_pk_bf16_f32 v163, v148, v149
	s_add_u32 s26, s24, 0x1000000
	s_addc_u32 s27, s25, 0
	global_store_dwordx4 v128, v[160:163], s[26:27]
	s_add_u32 s26, s20, 0x2000000
	s_addc_u32 s27, s21, 0
	global_load_dwordx4 v[0:3], v128, s[26:27]
	s_add_u32 s26, s20, 0x5000000
	s_addc_u32 s27, s21, 0
	global_load_dwordx4 v[4:7], v128, s[26:27]
	s_add_u32 s26, s20, 0x8000000
	s_addc_u32 s27, s21, 0
	global_load_dwordx4 v[8:11], v128, s[26:27]
	s_add_u32 s26, s22, 0x100000
	s_addc_u32 s27, s23, 0
	global_load_dword v12, v129, s[26:27]
	s_add_u32 s26, s22, 0x280000
	s_addc_u32 s27, s23, 0
	global_load_dword v13, v129, s[26:27]
	s_add_u32 s26, s22, 0x400000
	s_addc_u32 s27, s23, 0
	global_load_dword v14, v129, s[26:27]
	s_waitcnt vmcnt(49)
	v_max3_f32 v132, v28, v29, v30
	v_sub_f32_e32 v133, v28, v132
	v_sub_f32_e32 v134, v29, v132
	v_sub_f32_e32 v135, v30, v132
	v_mul_f32_e32 v133, 0x3fb8aa3b, v133
	v_mul_f32_e32 v134, 0x3fb8aa3b, v134
	v_mul_f32_e32 v135, 0x3fb8aa3b, v135
	v_exp_f32_e32 v133, v133
	v_exp_f32_e32 v134, v134
	v_exp_f32_e32 v135, v135
	s_nop 0
	v_add_f32_e32 v136, v133, v134
	v_add_f32_e32 v136, v135, v136
	v_div_scale_f32 v137, s[28:29], v136, v136, 1.0
	v_rcp_f32_e32 v138, v137
	v_div_scale_f32 v139, vcc, 1.0, v136, 1.0
	s_nop 0
	v_fma_f32 v140, -v137, v138, 1.0
	v_fmac_f32_e32 v138, v140, v138
	v_mul_f32_e32 v141, v139, v138
	v_fma_f32 v140, -v137, v141, v139
	v_fmac_f32_e32 v141, v140, v138
	v_fma_f32 v137, -v137, v141, v139
	v_div_fmas_f32 v137, v137, v138, v141
	v_div_fixup_f32 v136, v137, v136, 1.0
	v_mul_f32_e32 v133, v133, v136
	v_mul_f32_e32 v134, v134, v136
	v_mul_f32_e32 v135, v135, v136
	v_lshlrev_b32_e32 v142, 16, v16
	v_and_b32_e32 v145, 0xffff0000, v16
	v_lshlrev_b32_e32 v143, 16, v20
	v_and_b32_e32 v146, 0xffff0000, v20
	v_lshlrev_b32_e32 v144, 16, v24
	v_and_b32_e32 v147, 0xffff0000, v24
	v_mul_f32_e32 v148, v133, v142
	v_mul_f32_e32 v149, v133, v145
	v_fmac_f32_e32 v148, v134, v143
	v_fmac_f32_e32 v149, v134, v146
	v_fmac_f32_e32 v148, v135, v144
	v_fmac_f32_e32 v149, v135, v147
	v_cvt_pk_bf16_f32 v164, v148, v149
	v_lshlrev_b32_e32 v142, 16, v17
	v_and_b32_e32 v145, 0xffff0000, v17
	v_lshlrev_b32_e32 v143, 16, v21
	v_and_b32_e32 v146, 0xffff0000, v21
	v_lshlrev_b32_e32 v144, 16, v25
	v_and_b32_e32 v147, 0xffff0000, v25
	v_mul_f32_e32 v148, v133, v142
	v_mul_f32_e32 v149, v133, v145
	v_fmac_f32_e32 v148, v134, v143
	v_fmac_f32_e32 v149, v134, v146
	v_fmac_f32_e32 v148, v135, v144
	v_fmac_f32_e32 v149, v135, v147
	v_cvt_pk_bf16_f32 v165, v148, v149
	v_lshlrev_b32_e32 v142, 16, v18
	v_and_b32_e32 v145, 0xffff0000, v18
	v_lshlrev_b32_e32 v143, 16, v22
	v_and_b32_e32 v146, 0xffff0000, v22
	v_lshlrev_b32_e32 v144, 16, v26
	v_and_b32_e32 v147, 0xffff0000, v26
	v_mul_f32_e32 v148, v133, v142
	v_mul_f32_e32 v149, v133, v145
	v_fmac_f32_e32 v148, v134, v143
	v_fmac_f32_e32 v149, v134, v146
	v_fmac_f32_e32 v148, v135, v144
	v_fmac_f32_e32 v149, v135, v147
	v_cvt_pk_bf16_f32 v166, v148, v149
	v_lshlrev_b32_e32 v142, 16, v19
	v_and_b32_e32 v145, 0xffff0000, v19
	v_lshlrev_b32_e32 v143, 16, v23
	v_and_b32_e32 v146, 0xffff0000, v23
	v_lshlrev_b32_e32 v144, 16, v27
	v_and_b32_e32 v147, 0xffff0000, v27
	v_mul_f32_e32 v148, v133, v142
	v_mul_f32_e32 v149, v133, v145
	v_fmac_f32_e32 v148, v134, v143
	v_fmac_f32_e32 v149, v134, v146
	v_fmac_f32_e32 v148, v135, v144
	v_fmac_f32_e32 v149, v135, v147
	v_cvt_pk_bf16_f32 v167, v148, v149
	s_add_u32 s26, s24, 0x1200000
	s_addc_u32 s27, s25, 0
	global_store_dwordx4 v128, v[164:167], s[26:27]
	s_add_u32 s26, s20, 0x2200000
	s_addc_u32 s27, s21, 0
	global_load_dwordx4 v[16:19], v128, s[26:27]
	s_add_u32 s26, s20, 0x5200000
	s_addc_u32 s27, s21, 0
	global_load_dwordx4 v[20:23], v128, s[26:27]
	s_add_u32 s26, s20, 0x8200000
	s_addc_u32 s27, s21, 0
	global_load_dwordx4 v[24:27], v128, s[26:27]
	s_add_u32 s26, s22, 0x110000
	s_addc_u32 s27, s23, 0
	global_load_dword v28, v129, s[26:27]
	s_add_u32 s26, s22, 0x290000
	s_addc_u32 s27, s23, 0
	global_load_dword v29, v129, s[26:27]
	s_add_u32 s26, s22, 0x410000
	s_addc_u32 s27, s23, 0
	global_load_dword v30, v129, s[26:27]
	s_waitcnt vmcnt(49)
; __device__ __forceinline__ float bf_lo(unsigned w) { return __uint_as_float(w << 16); }
; __device__ __forceinline__ float bf_hi(unsigned w) { return __uint_as_float(w & 0xffff0000u); }
; __device__ __forceinline__ unsigned pk2(float lo, float hi) { return pg8::cvt_pk_bf16(lo, hi); }
; __device__ __forceinline__ void merge_rows(const Args& a, int gw, int NGW, int lane) {
;     const bf16* OG = (const bf16*)(a.ws + WS_OG); const float* LSE = (const float*)(a.ws + WS_LSE); bf16* YAT = (bf16*)(a.ws + WS_YAT);
;     const int hh = lane >> 4;
;     for (int mb = gw; mb < MT; mb += 4 * NGW) {
;         float l[4][3]; v2u o[4][3];
; #pragma unroll
;         for (int r = 0; r < 4; ++r) { const int m = mb + r * NGW; const int mc = m < MT ? m : mb;
; #pragma unroll
;             for (int g = 0; g < 3; ++g) { l[r][g] = LSE[((size_t)g * MT + mc) * 4 + hh]; o[r][g] = *(const v2u*)(OG + ((size_t)g * MT + mc) * 256 + 4 * lane); } }
; #pragma unroll
;         for (int r = 0; r < 4; ++r) { const int m = mb + r * NGW; if (m < MT) {
;             const float mxl = fmaxf(l[r][0], fmaxf(l[r][1], l[r][2]));
;             float a0 = __expf(l[r][0] - mxl), a1 = __expf(l[r][1] - mxl), a2 = __expf(l[r][2] - mxl); const float is = 1.0f / (a0 + a1 + a2); a0 *= is; a1 *= is; a2 *= is;
;             const v2u o0 = o[r][0], o1 = o[r][1], o2 = o[r][2];
;             v2u w;
;             w.x = pk2(a0 * pg8::bf_lo(o0.x) + a1 * pg8::bf_lo(o1.x) + a2 * pg8::bf_lo(o2.x), a0 * pg8::bf_hi(o0.x) + a1 * pg8::bf_hi(o1.x) + a2 * pg8::bf_hi(o2.x));
;             w.y = pk2(a0 * pg8::bf_lo(o0.y) + a1 * pg8::bf_lo(o1.y) + a2 * pg8::bf_lo(o2.y), a0 * pg8::bf_hi(o0.y) + a1 * pg8::bf_hi(o1.y) + a2 * pg8::bf_hi(o2.y));
;             *(v2u*)(YAT + (size_t)m * 256 + 4 * lane) = w; } }
;     }
; }
	v_max3_f32 v132, v44, v45, v46
	v_sub_f32_e32 v133, v44, v132
	v_sub_f32_e32 v134, v45, v132
	v_sub_f32_e32 v135, v46, v132
	v_mul_f32_e32 v133, 0x3fb8aa3b, v133
	v_mul_f32_e32 v134, 0x3fb8aa3b, v134
	v_mul_f32_e32 v135, 0x3fb8aa3b, v135
	v_exp_f32_e32 v133, v133
	v_exp_f32_e32 v134, v134
	v_exp_f32_e32 v135, v135
	s_nop 0
	v_add_f32_e32 v136, v133, v134
	v_add_f32_e32 v136, v135, v136
	v_div_scale_f32 v137, s[28:29], v136, v136, 1.0
	v_rcp_f32_e32 v138, v137
	v_div_scale_f32 v139, vcc, 1.0, v136, 1.0
	s_nop 0
	v_fma_f32 v140, -v137, v138, 1.0
	v_fmac_f32_e32 v138, v140, v138
	v_mul_f32_e32 v141, v139, v138
	v_fma_f32 v140, -v137, v141, v139
	v_fmac_f32_e32 v141, v140, v138
	v_fma_f32 v137, -v137, v141, v139
	v_div_fmas_f32 v137, v137, v138, v141
	v_div_fixup_f32 v136, v137, v136, 1.0
	v_mul_f32_e32 v133, v133, v136
	v_mul_f32_e32 v134, v134, v136
	v_mul_f32_e32 v135, v135, v136
	v_lshlrev_b32_e32 v142, 16, v32
	v_and_b32_e32 v145, 0xffff0000, v32
	v_lshlrev_b32_e32 v143, 16, v36
	v_and_b32_e32 v146, 0xffff0000, v36
	v_lshlrev_b32_e32 v144, 16, v40
	v_and_b32_e32 v147, 0xffff0000, v40
	v_mul_f32_e32 v148, v133, v142
	v_mul_f32_e32 v149, v133, v145
	v_fmac_f32_e32 v148, v134, v143
	v_fmac_f32_e32 v149, v134, v146
	v_fmac_f32_e32 v148, v135, v144
	v_fmac_f32_e32 v149, v135, v147
	v_cvt_pk_bf16_f32 v160, v148, v149
	v_lshlrev_b32_e32 v142, 16, v33
	v_and_b32_e32 v145, 0xffff0000, v33
	v_lshlrev_b32_e32 v143, 16, v37
	v_and_b32_e32 v146, 0xffff0000, v37
	v_lshlrev_b32_e32 v144, 16, v41
	v_and_b32_e32 v147, 0xffff0000, v41
	v_mul_f32_e32 v148, v133, v142
	v_mul_f32_e32 v149, v133, v145
	v_fmac_f32_e32 v148, v134, v143
	v_fmac_f32_e32 v149, v134, v146
	v_fmac_f32_e32 v148, v135, v144
	v_fmac_f32_e32 v149, v135, v147
	v_cvt_pk_bf16_f32 v161, v148, v149
	v_lshlrev_b32_e32 v142, 16, v34
	v_and_b32_e32 v145, 0xffff0000, v34
	v_lshlrev_b32_e32 v143, 16, v38
	v_and_b32_e32 v146, 0xffff0000, v38
	v_lshlrev_b32_e32 v144, 16, v42
	v_and_b32_e32 v147, 0xffff0000, v42
	v_mul_f32_e32 v148, v133, v142
	v_mul_f32_e32 v149, v133, v145
	v_fmac_f32_e32 v148, v134, v143
	v_fmac_f32_e32 v149, v134, v146
	v_fmac_f32_e32 v148, v135, v144
	v_fmac_f32_e32 v149, v135, v147
	v_cvt_pk_bf16_f32 v162, v148, v149
	v_lshlrev_b32_e32 v142, 16, v35
	v_and_b32_e32 v145, 0xffff0000, v35
	v_lshlrev_b32_e32 v143, 16, v39
	v_and_b32_e32 v146, 0xffff0000, v39
	v_lshlrev_b32_e32 v144, 16, v43
	v_and_b32_e32 v147, 0xffff0000, v43
	v_mul_f32_e32 v148, v133, v142
	v_mul_f32_e32 v149, v133, v145
	v_fmac_f32_e32 v148, v134, v143
	v_fmac_f32_e32 v149, v134, v146
	v_fmac_f32_e32 v148, v135, v144
	v_fmac_f32_e32 v149, v135, v147
	v_cvt_pk_bf16_f32 v163, v148, v149
	s_add_u32 s26, s24, 0x1400000
	s_addc_u32 s27, s25, 0
	global_store_dwordx4 v128, v[160:163], s[26:27]
	s_add_u32 s26, s20, 0x2400000
	s_addc_u32 s27, s21, 0
	global_load_dwordx4 v[32:35], v128, s[26:27]
	s_add_u32 s26, s20, 0x5400000
	s_addc_u32 s27, s21, 0
	global_load_dwordx4 v[36:39], v128, s[26:27]
	s_add_u32 s26, s20, 0x8400000
	s_addc_u32 s27, s21, 0
	global_load_dwordx4 v[40:43], v128, s[26:27]
	s_add_u32 s26, s22, 0x120000
	s_addc_u32 s27, s23, 0
	global_load_dword v44, v129, s[26:27]
	s_add_u32 s26, s22, 0x2a0000
	s_addc_u32 s27, s23, 0
	global_load_dword v45, v129, s[26:27]
	s_add_u32 s26, s22, 0x420000
	s_addc_u32 s27, s23, 0
	global_load_dword v46, v129, s[26:27]
	s_waitcnt vmcnt(49)
	v_max3_f32 v132, v60, v61, v62
	v_sub_f32_e32 v133, v60, v132
	v_sub_f32_e32 v134, v61, v132
	v_sub_f32_e32 v135, v62, v132
	v_mul_f32_e32 v133, 0x3fb8aa3b, v133
	v_mul_f32_e32 v134, 0x3fb8aa3b, v134
	v_mul_f32_e32 v135, 0x3fb8aa3b, v135
	v_exp_f32_e32 v133, v133
	v_exp_f32_e32 v134, v134
	v_exp_f32_e32 v135, v135
	s_nop 0
	v_add_f32_e32 v136, v133, v134
	v_add_f32_e32 v136, v135, v136
	v_div_scale_f32 v137, s[28:29], v136, v136, 1.0
	v_rcp_f32_e32 v138, v137
	v_div_scale_f32 v139, vcc, 1.0, v136, 1.0
	s_nop 0
	v_fma_f32 v140, -v137, v138, 1.0
	v_fmac_f32_e32 v138, v140, v138
	v_mul_f32_e32 v141, v139, v138
	v_fma_f32 v140, -v137, v141, v139
	v_fmac_f32_e32 v141, v140, v138
	v_fma_f32 v137, -v137, v141, v139
	v_div_fmas_f32 v137, v137, v138, v141
	v_div_fixup_f32 v136, v137, v136, 1.0
	v_mul_f32_e32 v133, v133, v136
	v_mul_f32_e32 v134, v134, v136
	v_mul_f32_e32 v135, v135, v136
	v_lshlrev_b32_e32 v142, 16, v48
	v_and_b32_e32 v145, 0xffff0000, v48
	v_lshlrev_b32_e32 v143, 16, v52
	v_and_b32_e32 v146, 0xffff0000, v52
	v_lshlrev_b32_e32 v144, 16, v56
	v_and_b32_e32 v147, 0xffff0000, v56
	v_mul_f32_e32 v148, v133, v142
	v_mul_f32_e32 v149, v133, v145
	v_fmac_f32_e32 v148, v134, v143
	v_fmac_f32_e32 v149, v134, v146
	v_fmac_f32_e32 v148, v135, v144
	v_fmac_f32_e32 v149, v135, v147
	v_cvt_pk_bf16_f32 v164, v148, v149
	v_lshlrev_b32_e32 v142, 16, v49
	v_and_b32_e32 v145, 0xffff0000, v49
	v_lshlrev_b32_e32 v143, 16, v53
	v_and_b32_e32 v146, 0xffff0000, v53
	v_lshlrev_b32_e32 v144, 16, v57
	v_and_b32_e32 v147, 0xffff0000, v57
	v_mul_f32_e32 v148, v133, v142
	v_mul_f32_e32 v149, v133, v145
	v_fmac_f32_e32 v148, v134, v143
	v_fmac_f32_e32 v149, v134, v146
	v_fmac_f32_e32 v148, v135, v144
	v_fmac_f32_e32 v149, v135, v147
	v_cvt_pk_bf16_f32 v165, v148, v149
	v_lshlrev_b32_e32 v142, 16, v50
	v_and_b32_e32 v145, 0xffff0000, v50
	v_lshlrev_b32_e32 v143, 16, v54
	v_and_b32_e32 v146, 0xffff0000, v54
	v_lshlrev_b32_e32 v144, 16, v58
	v_and_b32_e32 v147, 0xffff0000, v58
	v_mul_f32_e32 v148, v133, v142
	v_mul_f32_e32 v149, v133, v145
	v_fmac_f32_e32 v148, v134, v143
	v_fmac_f32_e32 v149, v134, v146
	v_fmac_f32_e32 v148, v135, v144
	v_fmac_f32_e32 v149, v135, v147
	v_cvt_pk_bf16_f32 v166, v148, v149
	v_lshlrev_b32_e32 v142, 16, v51
	v_and_b32_e32 v145, 0xffff0000, v51
	v_lshlrev_b32_e32 v143, 16, v55
	v_and_b32_e32 v146, 0xffff0000, v55
	v_lshlrev_b32_e32 v144, 16, v59
	v_and_b32_e32 v147, 0xffff0000, v59
	v_mul_f32_e32 v148, v133, v142
	v_mul_f32_e32 v149, v133, v145
	v_fmac_f32_e32 v148, v134, v143
	v_fmac_f32_e32 v149, v134, v146
	v_fmac_f32_e32 v148, v135, v144
	v_fmac_f32_e32 v149, v135, v147
	v_cvt_pk_bf16_f32 v167, v148, v149
	s_add_u32 s26, s24, 0x1600000
	s_addc_u32 s27, s25, 0
	global_store_dwordx4 v128, v[164:167], s[26:27]
	s_add_u32 s26, s20, 0x2600000
	s_addc_u32 s27, s21, 0
	global_load_dwordx4 v[48:51], v128, s[26:27]
	s_add_u32 s26, s20, 0x5600000
	s_addc_u32 s27, s21, 0
	global_load_dwordx4 v[52:55], v128, s[26:27]
	s_add_u32 s26, s20, 0x8600000
	s_addc_u32 s27, s21, 0
	global_load_dwordx4 v[56:59], v128, s[26:27]
	s_add_u32 s26, s22, 0x130000
	s_addc_u32 s27, s23, 0
	global_load_dword v60, v129, s[26:27]
	s_add_u32 s26, s22, 0x2b0000
	s_addc_u32 s27, s23, 0
	global_load_dword v61, v129, s[26:27]
	s_add_u32 s26, s22, 0x430000
	s_addc_u32 s27, s23, 0
	global_load_dword v62, v129, s[26:27]
	s_waitcnt vmcnt(49)
; __device__ __forceinline__ float bf_lo(unsigned w) { return __uint_as_float(w << 16); }
; __device__ __forceinline__ float bf_hi(unsigned w) { return __uint_as_float(w & 0xffff0000u); }
; __device__ __forceinline__ unsigned pk2(float lo, float hi) { return pg8::cvt_pk_bf16(lo, hi); }
; __device__ __forceinline__ void merge_rows(const Args& a, int gw, int NGW, int lane) {
;     const bf16* OG = (const bf16*)(a.ws + WS_OG); const float* LSE = (const float*)(a.ws + WS_LSE); bf16* YAT = (bf16*)(a.ws + WS_YAT);
;     const int hh = lane >> 4;
;     for (int mb = gw; mb < MT; mb += 4 * NGW) {
;         float l[4][3]; v2u o[4][3];
; #pragma unroll
;         for (int r = 0; r < 4; ++r) { const int m = mb + r * NGW; const int mc = m < MT ? m : mb;
; #pragma unroll
;             for (int g = 0; g < 3; ++g) { l[r][g] = LSE[((size_t)g * MT + mc) * 4 + hh]; o[r][g] = *(const v2u*)(OG + ((size_t)g * MT + mc) * 256 + 4 * lane); } }
; #pragma unroll
;         for (int r = 0; r < 4; ++r) { const int m = mb + r * NGW; if (m < MT) {
;             const float mxl = fmaxf(l[r][0], fmaxf(l[r][1], l[r][2]));
;             float a0 = __expf(l[r][0] - mxl), a1 = __expf(l[r][1] - mxl), a2 = __expf(l[r][2] - mxl); const float is = 1.0f / (a0 + a1 + a2); a0 *= is; a1 *= is; a2 *= is;
;             const v2u o0 = o[r][0], o1 = o[r][1], o2 = o[r][2];
;             v2u w;
;             w.x = pk2(a0 * pg8::bf_lo(o0.x) + a1 * pg8::bf_lo(o1.x) + a2 * pg8::bf_lo(o2.x), a0 * pg8::bf_hi(o0.x) + a1 * pg8::bf_hi(o1.x) + a2 * pg8::bf_hi(o2.x));
;             w.y = pk2(a0 * pg8::bf_lo(o0.y) + a1 * pg8::bf_lo(o1.y) + a2 * pg8::bf_lo(o2.y), a0 * pg8::bf_hi(o0.y) + a1 * pg8::bf_hi(o1.y) + a2 * pg8::bf_hi(o2.y));
;             *(v2u*)(YAT + (size_t)m * 256 + 4 * lane) = w; } }
;     }
; }
	v_max3_f32 v132, v76, v77, v78
	v_sub_f32_e32 v133, v76, v132
	v_sub_f32_e32 v134, v77, v132
	v_sub_f32_e32 v135, v78, v132
	v_mul_f32_e32 v133, 0x3fb8aa3b, v133
	v_mul_f32_e32 v134, 0x3fb8aa3b, v134
	v_mul_f32_e32 v135, 0x3fb8aa3b, v135
	v_exp_f32_e32 v133, v133
	v_exp_f32_e32 v134, v134
	v_exp_f32_e32 v135, v135
	s_nop 0
	v_add_f32_e32 v136, v133, v134
	v_add_f32_e32 v136, v135, v136
	v_div_scale_f32 v137, s[28:29], v136, v136, 1.0
	v_rcp_f32_e32 v138, v137
	v_div_scale_f32 v139, vcc, 1.0, v136, 1.0
	s_nop 0
	v_fma_f32 v140, -v137, v138, 1.0
	v_fmac_f32_e32 v138, v140, v138
	v_mul_f32_e32 v141, v139, v138
	v_fma_f32 v140, -v137, v141, v139
	v_fmac_f32_e32 v141, v140, v138
	v_fma_f32 v137, -v137, v141, v139
	v_div_fmas_f32 v137, v137, v138, v141
	v_div_fixup_f32 v136, v137, v136, 1.0
	v_mul_f32_e32 v133, v133, v136
	v_mul_f32_e32 v134, v134, v136
	v_mul_f32_e32 v135, v135, v136
	v_lshlrev_b32_e32 v142, 16, v64
	v_and_b32_e32 v145, 0xffff0000, v64
	v_lshlrev_b32_e32 v143, 16, v68
	v_and_b32_e32 v146, 0xffff0000, v68
	v_lshlrev_b32_e32 v144, 16, v72
	v_and_b32_e32 v147, 0xffff0000, v72
	v_mul_f32_e32 v148, v133, v142
	v_mul_f32_e32 v149, v133, v145
	v_fmac_f32_e32 v148, v134, v143
	v_fmac_f32_e32 v149, v134, v146
	v_fmac_f32_e32 v148, v135, v144
	v_fmac_f32_e32 v149, v135, v147
	v_cvt_pk_bf16_f32 v160, v148, v149
	v_lshlrev_b32_e32 v142, 16, v65
	v_and_b32_e32 v145, 0xffff0000, v65
	v_lshlrev_b32_e32 v143, 16, v69
	v_and_b32_e32 v146, 0xffff0000, v69
	v_lshlrev_b32_e32 v144, 16, v73
	v_and_b32_e32 v147, 0xffff0000, v73
	v_mul_f32_e32 v148, v133, v142
	v_mul_f32_e32 v149, v133, v145
	v_fmac_f32_e32 v148, v134, v143
	v_fmac_f32_e32 v149, v134, v146
	v_fmac_f32_e32 v148, v135, v144
	v_fmac_f32_e32 v149, v135, v147
	v_cvt_pk_bf16_f32 v161, v148, v149
	v_lshlrev_b32_e32 v142, 16, v66
	v_and_b32_e32 v145, 0xffff0000, v66
	v_lshlrev_b32_e32 v143, 16, v70
	v_and_b32_e32 v146, 0xffff0000, v70
	v_lshlrev_b32_e32 v144, 16, v74
	v_and_b32_e32 v147, 0xffff0000, v74
	v_mul_f32_e32 v148, v133, v142
	v_mul_f32_e32 v149, v133, v145
	v_fmac_f32_e32 v148, v134, v143
	v_fmac_f32_e32 v149, v134, v146
	v_fmac_f32_e32 v148, v135, v144
	v_fmac_f32_e32 v149, v135, v147
	v_cvt_pk_bf16_f32 v162, v148, v149
	v_lshlrev_b32_e32 v142, 16, v67
	v_and_b32_e32 v145, 0xffff0000, v67
	v_lshlrev_b32_e32 v143, 16, v71
	v_and_b32_e32 v146, 0xffff0000, v71
	v_lshlrev_b32_e32 v144, 16, v75
	v_and_b32_e32 v147, 0xffff0000, v75
	v_mul_f32_e32 v148, v133, v142
	v_mul_f32_e32 v149, v133, v145
	v_fmac_f32_e32 v148, v134, v143
	v_fmac_f32_e32 v149, v134, v146
	v_fmac_f32_e32 v148, v135, v144
	v_fmac_f32_e32 v149, v135, v147
	v_cvt_pk_bf16_f32 v163, v148, v149
	s_add_u32 s26, s24, 0x1800000
	s_addc_u32 s27, s25, 0
	global_store_dwordx4 v128, v[160:163], s[26:27]
	s_add_u32 s26, s20, 0x2800000
	s_addc_u32 s27, s21, 0
	global_load_dwordx4 v[64:67], v128, s[26:27]
	s_add_u32 s26, s20, 0x5800000
	s_addc_u32 s27, s21, 0
	global_load_dwordx4 v[68:71], v128, s[26:27]
	s_add_u32 s26, s20, 0x8800000
	s_addc_u32 s27, s21, 0
	global_load_dwordx4 v[72:75], v128, s[26:27]
	s_add_u32 s26, s22, 0x140000
	s_addc_u32 s27, s23, 0
	global_load_dword v76, v129, s[26:27]
	s_add_u32 s26, s22, 0x2c0000
	s_addc_u32 s27, s23, 0
	global_load_dword v77, v129, s[26:27]
	s_add_u32 s26, s22, 0x440000
	s_addc_u32 s27, s23, 0
	global_load_dword v78, v129, s[26:27]
	s_waitcnt vmcnt(49)
	v_max3_f32 v132, v92, v93, v94
	v_sub_f32_e32 v133, v92, v132
	v_sub_f32_e32 v134, v93, v132
	v_sub_f32_e32 v135, v94, v132
	v_mul_f32_e32 v133, 0x3fb8aa3b, v133
	v_mul_f32_e32 v134, 0x3fb8aa3b, v134
	v_mul_f32_e32 v135, 0x3fb8aa3b, v135
	v_exp_f32_e32 v133, v133
	v_exp_f32_e32 v134, v134
	v_exp_f32_e32 v135, v135
	s_nop 0
	v_add_f32_e32 v136, v133, v134
	v_add_f32_e32 v136, v135, v136
	v_div_scale_f32 v137, s[28:29], v136, v136, 1.0
	v_rcp_f32_e32 v138, v137
	v_div_scale_f32 v139, vcc, 1.0, v136, 1.0
	s_nop 0
	v_fma_f32 v140, -v137, v138, 1.0
	v_fmac_f32_e32 v138, v140, v138
	v_mul_f32_e32 v141, v139, v138
	v_fma_f32 v140, -v137, v141, v139
	v_fmac_f32_e32 v141, v140, v138
	v_fma_f32 v137, -v137, v141, v139
	v_div_fmas_f32 v137, v137, v138, v141
	v_div_fixup_f32 v136, v137, v136, 1.0
	v_mul_f32_e32 v133, v133, v136
	v_mul_f32_e32 v134, v134, v136
	v_mul_f32_e32 v135, v135, v136
	v_lshlrev_b32_e32 v142, 16, v80
	v_and_b32_e32 v145, 0xffff0000, v80
	v_lshlrev_b32_e32 v143, 16, v84
	v_and_b32_e32 v146, 0xffff0000, v84
	v_lshlrev_b32_e32 v144, 16, v88
	v_and_b32_e32 v147, 0xffff0000, v88
	v_mul_f32_e32 v148, v133, v142
	v_mul_f32_e32 v149, v133, v145
	v_fmac_f32_e32 v148, v134, v143
	v_fmac_f32_e32 v149, v134, v146
	v_fmac_f32_e32 v148, v135, v144
	v_fmac_f32_e32 v149, v135, v147
	v_cvt_pk_bf16_f32 v164, v148, v149
	v_lshlrev_b32_e32 v142, 16, v81
	v_and_b32_e32 v145, 0xffff0000, v81
	v_lshlrev_b32_e32 v143, 16, v85
	v_and_b32_e32 v146, 0xffff0000, v85
	v_lshlrev_b32_e32 v144, 16, v89
	v_and_b32_e32 v147, 0xffff0000, v89
	v_mul_f32_e32 v148, v133, v142
	v_mul_f32_e32 v149, v133, v145
	v_fmac_f32_e32 v148, v134, v143
	v_fmac_f32_e32 v149, v134, v146
	v_fmac_f32_e32 v148, v135, v144
	v_fmac_f32_e32 v149, v135, v147
	v_cvt_pk_bf16_f32 v165, v148, v149
	v_lshlrev_b32_e32 v142, 16, v82
	v_and_b32_e32 v145, 0xffff0000, v82
	v_lshlrev_b32_e32 v143, 16, v86
	v_and_b32_e32 v146, 0xffff0000, v86
	v_lshlrev_b32_e32 v144, 16, v90
	v_and_b32_e32 v147, 0xffff0000, v90
	v_mul_f32_e32 v148, v133, v142
	v_mul_f32_e32 v149, v133, v145
	v_fmac_f32_e32 v148, v134, v143
	v_fmac_f32_e32 v149, v134, v146
	v_fmac_f32_e32 v148, v135, v144
	v_fmac_f32_e32 v149, v135, v147
	v_cvt_pk_bf16_f32 v166, v148, v149
	v_lshlrev_b32_e32 v142, 16, v83
	v_and_b32_e32 v145, 0xffff0000, v83
	v_lshlrev_b32_e32 v143, 16, v87
	v_and_b32_e32 v146, 0xffff0000, v87
	v_lshlrev_b32_e32 v144, 16, v91
	v_and_b32_e32 v147, 0xffff0000, v91
	v_mul_f32_e32 v148, v133, v142
	v_mul_f32_e32 v149, v133, v145
	v_fmac_f32_e32 v148, v134, v143
	v_fmac_f32_e32 v149, v134, v146
	v_fmac_f32_e32 v148, v135, v144
	v_fmac_f32_e32 v149, v135, v147
	v_cvt_pk_bf16_f32 v167, v148, v149
	s_add_u32 s26, s24, 0x1a00000
	s_addc_u32 s27, s25, 0
	global_store_dwordx4 v128, v[164:167], s[26:27]
	s_add_u32 s26, s20, 0x2a00000
	s_addc_u32 s27, s21, 0
	global_load_dwordx4 v[80:83], v128, s[26:27]
	s_add_u32 s26, s20, 0x5a00000
	s_addc_u32 s27, s21, 0
	global_load_dwordx4 v[84:87], v128, s[26:27]
	s_add_u32 s26, s20, 0x8a00000
	s_addc_u32 s27, s21, 0
	global_load_dwordx4 v[88:91], v128, s[26:27]
	s_add_u32 s26, s22, 0x150000
	s_addc_u32 s27, s23, 0
	global_load_dword v92, v129, s[26:27]
	s_add_u32 s26, s22, 0x2d0000
	s_addc_u32 s27, s23, 0
	global_load_dword v93, v129, s[26:27]
	s_add_u32 s26, s22, 0x450000
	s_addc_u32 s27, s23, 0
	global_load_dword v94, v129, s[26:27]
	s_waitcnt vmcnt(49)
; __device__ __forceinline__ float bf_lo(unsigned w) { return __uint_as_float(w << 16); }
; __device__ __forceinline__ float bf_hi(unsigned w) { return __uint_as_float(w & 0xffff0000u); }
; __device__ __forceinline__ unsigned pk2(float lo, float hi) { return pg8::cvt_pk_bf16(lo, hi); }
; __device__ __forceinline__ void merge_rows(const Args& a, int gw, int NGW, int lane) {
;     const bf16* OG = (const bf16*)(a.ws + WS_OG); const float* LSE = (const float*)(a.ws + WS_LSE); bf16* YAT = (bf16*)(a.ws + WS_YAT);
;     const int hh = lane >> 4;
;     for (int mb = gw; mb < MT; mb += 4 * NGW) {
;         float l[4][3]; v2u o[4][3];
; #pragma unroll
;         for (int r = 0; r < 4; ++r) { const int m = mb + r * NGW; const int mc = m < MT ? m : mb;
; #pragma unroll
;             for (int g = 0; g < 3; ++g) { l[r][g] = LSE[((size_t)g * MT + mc) * 4 + hh]; o[r][g] = *(const v2u*)(OG + ((size_t)g * MT + mc) * 256 + 4 * lane); } }
; #pragma unroll
;         for (int r = 0; r < 4; ++r) { const int m = mb + r * NGW; if (m < MT) {
;             const float mxl = fmaxf(l[r][0], fmaxf(l[r][1], l[r][2]));
;             float a0 = __expf(l[r][0] - mxl), a1 = __expf(l[r][1] - mxl), a2 = __expf(l[r][2] - mxl); const float is = 1.0f / (a0 + a1 + a2); a0 *= is; a1 *= is; a2 *= is;
;             const v2u o0 = o[r][0], o1 = o[r][1], o2 = o[r][2];
;             v2u w;
;             w.x = pk2(a0 * pg8::bf_lo(o0.x) + a1 * pg8::bf_lo(o1.x) + a2 * pg8::bf_lo(o2.x), a0 * pg8::bf_hi(o0.x) + a1 * pg8::bf_hi(o1.x) + a2 * pg8::bf_hi(o2.x));
;             w.y = pk2(a0 * pg8::bf_lo(o0.y) + a1 * pg8::bf_lo(o1.y) + a2 * pg8::bf_lo(o2.y), a0 * pg8::bf_hi(o0.y) + a1 * pg8::bf_hi(o1.y) + a2 * pg8::bf_hi(o2.y));
;             *(v2u*)(YAT + (size_t)m * 256 + 4 * lane) = w; } }
;     }
; }
	v_max3_f32 v132, v108, v109, v110
	v_sub_f32_e32 v133, v108, v132
	v_sub_f32_e32 v134, v109, v132
	v_sub_f32_e32 v135, v110, v132
	v_mul_f32_e32 v133, 0x3fb8aa3b, v133
	v_mul_f32_e32 v134, 0x3fb8aa3b, v134
	v_mul_f32_e32 v135, 0x3fb8aa3b, v135
	v_exp_f32_e32 v133, v133
	v_exp_f32_e32 v134, v134
	v_exp_f32_e32 v135, v135
	s_nop 0
	v_add_f32_e32 v136, v133, v134
	v_add_f32_e32 v136, v135, v136
	v_div_scale_f32 v137, s[28:29], v136, v136, 1.0
	v_rcp_f32_e32 v138, v137
	v_div_scale_f32 v139, vcc, 1.0, v136, 1.0
	s_nop 0
	v_fma_f32 v140, -v137, v138, 1.0
	v_fmac_f32_e32 v138, v140, v138
	v_mul_f32_e32 v141, v139, v138
	v_fma_f32 v140, -v137, v141, v139
	v_fmac_f32_e32 v141, v140, v138
	v_fma_f32 v137, -v137, v141, v139
	v_div_fmas_f32 v137, v137, v138, v141
	v_div_fixup_f32 v136, v137, v136, 1.0
	v_mul_f32_e32 v133, v133, v136
	v_mul_f32_e32 v134, v134, v136
	v_mul_f32_e32 v135, v135, v136
	v_lshlrev_b32_e32 v142, 16, v96
	v_and_b32_e32 v145, 0xffff0000, v96
	v_lshlrev_b32_e32 v143, 16, v100
	v_and_b32_e32 v146, 0xffff0000, v100
	v_lshlrev_b32_e32 v144, 16, v104
	v_and_b32_e32 v147, 0xffff0000, v104
	v_mul_f32_e32 v148, v133, v142
	v_mul_f32_e32 v149, v133, v145
	v_fmac_f32_e32 v148, v134, v143
	v_fmac_f32_e32 v149, v134, v146
	v_fmac_f32_e32 v148, v135, v144
	v_fmac_f32_e32 v149, v135, v147
	v_cvt_pk_bf16_f32 v160, v148, v149
	v_lshlrev_b32_e32 v142, 16, v97
	v_and_b32_e32 v145, 0xffff0000, v97
	v_lshlrev_b32_e32 v143, 16, v101
	v_and_b32_e32 v146, 0xffff0000, v101
	v_lshlrev_b32_e32 v144, 16, v105
	v_and_b32_e32 v147, 0xffff0000, v105
	v_mul_f32_e32 v148, v133, v142
	v_mul_f32_e32 v149, v133, v145
	v_fmac_f32_e32 v148, v134, v143
	v_fmac_f32_e32 v149, v134, v146
	v_fmac_f32_e32 v148, v135, v144
	v_fmac_f32_e32 v149, v135, v147
	v_cvt_pk_bf16_f32 v161, v148, v149
	v_lshlrev_b32_e32 v142, 16, v98
	v_and_b32_e32 v145, 0xffff0000, v98
	v_lshlrev_b32_e32 v143, 16, v102
	v_and_b32_e32 v146, 0xffff0000, v102
	v_lshlrev_b32_e32 v144, 16, v106
	v_and_b32_e32 v147, 0xffff0000, v106
	v_mul_f32_e32 v148, v133, v142
	v_mul_f32_e32 v149, v133, v145
	v_fmac_f32_e32 v148, v134, v143
	v_fmac_f32_e32 v149, v134, v146
	v_fmac_f32_e32 v148, v135, v144
	v_fmac_f32_e32 v149, v135, v147
	v_cvt_pk_bf16_f32 v162, v148, v149
	v_lshlrev_b32_e32 v142, 16, v99
	v_and_b32_e32 v145, 0xffff0000, v99
	v_lshlrev_b32_e32 v143, 16, v103
	v_and_b32_e32 v146, 0xffff0000, v103
	v_lshlrev_b32_e32 v144, 16, v107
	v_and_b32_e32 v147, 0xffff0000, v107
	v_mul_f32_e32 v148, v133, v142
	v_mul_f32_e32 v149, v133, v145
	v_fmac_f32_e32 v148, v134, v143
	v_fmac_f32_e32 v149, v134, v146
	v_fmac_f32_e32 v148, v135, v144
	v_fmac_f32_e32 v149, v135, v147
	v_cvt_pk_bf16_f32 v163, v148, v149
	s_add_u32 s26, s24, 0x1c00000
	s_addc_u32 s27, s25, 0
	global_store_dwordx4 v128, v[160:163], s[26:27]
	s_add_u32 s26, s20, 0x2c00000
	s_addc_u32 s27, s21, 0
	global_load_dwordx4 v[96:99], v128, s[26:27]
	s_add_u32 s26, s20, 0x5c00000
	s_addc_u32 s27, s21, 0
	global_load_dwordx4 v[100:103], v128, s[26:27]
	s_add_u32 s26, s20, 0x8c00000
	s_addc_u32 s27, s21, 0
	global_load_dwordx4 v[104:107], v128, s[26:27]
	s_add_u32 s26, s22, 0x160000
	s_addc_u32 s27, s23, 0
	global_load_dword v108, v129, s[26:27]
	s_add_u32 s26, s22, 0x2e0000
	s_addc_u32 s27, s23, 0
	global_load_dword v109, v129, s[26:27]
	s_add_u32 s26, s22, 0x460000
	s_addc_u32 s27, s23, 0
	global_load_dword v110, v129, s[26:27]
	s_waitcnt vmcnt(49)
	v_max3_f32 v132, v124, v125, v126
	v_sub_f32_e32 v133, v124, v132
	v_sub_f32_e32 v134, v125, v132
	v_sub_f32_e32 v135, v126, v132
	v_mul_f32_e32 v133, 0x3fb8aa3b, v133
	v_mul_f32_e32 v134, 0x3fb8aa3b, v134
	v_mul_f32_e32 v135, 0x3fb8aa3b, v135
	v_exp_f32_e32 v133, v133
	v_exp_f32_e32 v134, v134
	v_exp_f32_e32 v135, v135
	s_nop 0
	v_add_f32_e32 v136, v133, v134
	v_add_f32_e32 v136, v135, v136
	v_div_scale_f32 v137, s[28:29], v136, v136, 1.0
	v_rcp_f32_e32 v138, v137
	v_div_scale_f32 v139, vcc, 1.0, v136, 1.0
	s_nop 0
	v_fma_f32 v140, -v137, v138, 1.0
	v_fmac_f32_e32 v138, v140, v138
	v_mul_f32_e32 v141, v139, v138
	v_fma_f32 v140, -v137, v141, v139
	v_fmac_f32_e32 v141, v140, v138
	v_fma_f32 v137, -v137, v141, v139
	v_div_fmas_f32 v137, v137, v138, v141
	v_div_fixup_f32 v136, v137, v136, 1.0
	v_mul_f32_e32 v133, v133, v136
	v_mul_f32_e32 v134, v134, v136
	v_mul_f32_e32 v135, v135, v136
	v_lshlrev_b32_e32 v142, 16, v112
	v_and_b32_e32 v145, 0xffff0000, v112
	v_lshlrev_b32_e32 v143, 16, v116
	v_and_b32_e32 v146, 0xffff0000, v116
	v_lshlrev_b32_e32 v144, 16, v120
	v_and_b32_e32 v147, 0xffff0000, v120
	v_mul_f32_e32 v148, v133, v142
	v_mul_f32_e32 v149, v133, v145
	v_fmac_f32_e32 v148, v134, v143
	v_fmac_f32_e32 v149, v134, v146
	v_fmac_f32_e32 v148, v135, v144
	v_fmac_f32_e32 v149, v135, v147
	v_cvt_pk_bf16_f32 v164, v148, v149
	v_lshlrev_b32_e32 v142, 16, v113
	v_and_b32_e32 v145, 0xffff0000, v113
	v_lshlrev_b32_e32 v143, 16, v117
	v_and_b32_e32 v146, 0xffff0000, v117
	v_lshlrev_b32_e32 v144, 16, v121
	v_and_b32_e32 v147, 0xffff0000, v121
	v_mul_f32_e32 v148, v133, v142
	v_mul_f32_e32 v149, v133, v145
	v_fmac_f32_e32 v148, v134, v143
	v_fmac_f32_e32 v149, v134, v146
	v_fmac_f32_e32 v148, v135, v144
	v_fmac_f32_e32 v149, v135, v147
	v_cvt_pk_bf16_f32 v165, v148, v149
	v_lshlrev_b32_e32 v142, 16, v114
	v_and_b32_e32 v145, 0xffff0000, v114
	v_lshlrev_b32_e32 v143, 16, v118
	v_and_b32_e32 v146, 0xffff0000, v118
	v_lshlrev_b32_e32 v144, 16, v122
	v_and_b32_e32 v147, 0xffff0000, v122
	v_mul_f32_e32 v148, v133, v142
	v_mul_f32_e32 v149, v133, v145
	v_fmac_f32_e32 v148, v134, v143
	v_fmac_f32_e32 v149, v134, v146
	v_fmac_f32_e32 v148, v135, v144
	v_fmac_f32_e32 v149, v135, v147
	v_cvt_pk_bf16_f32 v166, v148, v149
	v_lshlrev_b32_e32 v142, 16, v115
	v_and_b32_e32 v145, 0xffff0000, v115
	v_lshlrev_b32_e32 v143, 16, v119
	v_and_b32_e32 v146, 0xffff0000, v119
	v_lshlrev_b32_e32 v144, 16, v123
	v_and_b32_e32 v147, 0xffff0000, v123
	v_mul_f32_e32 v148, v133, v142
	v_mul_f32_e32 v149, v133, v145
	v_fmac_f32_e32 v148, v134, v143
	v_fmac_f32_e32 v149, v134, v146
	v_fmac_f32_e32 v148, v135, v144
	v_fmac_f32_e32 v149, v135, v147
	v_cvt_pk_bf16_f32 v167, v148, v149
	s_add_u32 s26, s24, 0x1e00000
	s_addc_u32 s27, s25, 0
	global_store_dwordx4 v128, v[164:167], s[26:27]
	s_add_u32 s26, s20, 0x2e00000
	s_addc_u32 s27, s21, 0
	global_load_dwordx4 v[112:115], v128, s[26:27]
	s_add_u32 s26, s20, 0x5e00000
	s_addc_u32 s27, s21, 0
	global_load_dwordx4 v[116:119], v128, s[26:27]
	s_add_u32 s26, s20, 0x8e00000
	s_addc_u32 s27, s21, 0
	global_load_dwordx4 v[120:123], v128, s[26:27]
	s_add_u32 s26, s22, 0x170000
	s_addc_u32 s27, s23, 0
	global_load_dword v124, v129, s[26:27]
	s_add_u32 s26, s22, 0x2f0000
	s_addc_u32 s27, s23, 0
	global_load_dword v125, v129, s[26:27]
	s_add_u32 s26, s22, 0x470000
	s_addc_u32 s27, s23, 0
	global_load_dword v126, v129, s[26:27]
	s_waitcnt vmcnt(49)
; __device__ __forceinline__ float bf_lo(unsigned w) { return __uint_as_float(w << 16); }
; __device__ __forceinline__ float bf_hi(unsigned w) { return __uint_as_float(w & 0xffff0000u); }
; __device__ __forceinline__ unsigned pk2(float lo, float hi) { return pg8::cvt_pk_bf16(lo, hi); }
; __device__ __forceinline__ void merge_rows(const Args& a, int gw, int NGW, int lane) {
;     const bf16* OG = (const bf16*)(a.ws + WS_OG); const float* LSE = (const float*)(a.ws + WS_LSE); bf16* YAT = (bf16*)(a.ws + WS_YAT);
;     const int hh = lane >> 4;
;     for (int mb = gw; mb < MT; mb += 4 * NGW) {
;         float l[4][3]; v2u o[4][3];
; #pragma unroll
;         for (int r = 0; r < 4; ++r) { const int m = mb + r * NGW; const int mc = m < MT ? m : mb;
; #pragma unroll
;             for (int g = 0; g < 3; ++g) { l[r][g] = LSE[((size_t)g * MT + mc) * 4 + hh]; o[r][g] = *(const v2u*)(OG + ((size_t)g * MT + mc) * 256 + 4 * lane); } }
; #pragma unroll
;         for (int r = 0; r < 4; ++r) { const int m = mb + r * NGW; if (m < MT) {
;             const float mxl = fmaxf(l[r][0], fmaxf(l[r][1], l[r][2]));
;             float a0 = __expf(l[r][0] - mxl), a1 = __expf(l[r][1] - mxl), a2 = __expf(l[r][2] - mxl); const float is = 1.0f / (a0 + a1 + a2); a0 *= is; a1 *= is; a2 *= is;
;             const v2u o0 = o[r][0], o1 = o[r][1], o2 = o[r][2];
;             v2u w;
;             w.x = pk2(a0 * pg8::bf_lo(o0.x) + a1 * pg8::bf_lo(o1.x) + a2 * pg8::bf_lo(o2.x), a0 * pg8::bf_hi(o0.x) + a1 * pg8::bf_hi(o1.x) + a2 * pg8::bf_hi(o2.x));
;             w.y = pk2(a0 * pg8::bf_lo(o0.y) + a1 * pg8::bf_lo(o1.y) + a2 * pg8::bf_lo(o2.y), a0 * pg8::bf_hi(o0.y) + a1 * pg8::bf_hi(o1.y) + a2 * pg8::bf_hi(o2.y));
;             *(v2u*)(YAT + (size_t)m * 256 + 4 * lane) = w; } }
;     }
; }
	v_max3_f32 v132, v12, v13, v14
	v_sub_f32_e32 v133, v12, v132
	v_sub_f32_e32 v134, v13, v132
	v_sub_f32_e32 v135, v14, v132
	v_mul_f32_e32 v133, 0x3fb8aa3b, v133
	v_mul_f32_e32 v134, 0x3fb8aa3b, v134
	v_mul_f32_e32 v135, 0x3fb8aa3b, v135
	v_exp_f32_e32 v133, v133
	v_exp_f32_e32 v134, v134
	v_exp_f32_e32 v135, v135
	s_nop 0
	v_add_f32_e32 v136, v133, v134
	v_add_f32_e32 v136, v135, v136
	v_div_scale_f32 v137, s[28:29], v136, v136, 1.0
	v_rcp_f32_e32 v138, v137
	v_div_scale_f32 v139, vcc, 1.0, v136, 1.0
	s_nop 0
	v_fma_f32 v140, -v137, v138, 1.0
	v_fmac_f32_e32 v138, v140, v138
	v_mul_f32_e32 v141, v139, v138
	v_fma_f32 v140, -v137, v141, v139
	v_fmac_f32_e32 v141, v140, v138
	v_fma_f32 v137, -v137, v141, v139
	v_div_fmas_f32 v137, v137, v138, v141
	v_div_fixup_f32 v136, v137, v136, 1.0
	v_mul_f32_e32 v133, v133, v136
	v_mul_f32_e32 v134, v134, v136
	v_mul_f32_e32 v135, v135, v136
	v_lshlrev_b32_e32 v142, 16, v0
	v_and_b32_e32 v145, 0xffff0000, v0
	v_lshlrev_b32_e32 v143, 16, v4
	v_and_b32_e32 v146, 0xffff0000, v4
	v_lshlrev_b32_e32 v144, 16, v8
	v_and_b32_e32 v147, 0xffff0000, v8
	v_mul_f32_e32 v148, v133, v142
	v_mul_f32_e32 v149, v133, v145
	v_fmac_f32_e32 v148, v134, v143
	v_fmac_f32_e32 v149, v134, v146
	v_fmac_f32_e32 v148, v135, v144
	v_fmac_f32_e32 v149, v135, v147
	v_cvt_pk_bf16_f32 v160, v148, v149
	v_lshlrev_b32_e32 v142, 16, v1
	v_and_b32_e32 v145, 0xffff0000, v1
	v_lshlrev_b32_e32 v143, 16, v5
	v_and_b32_e32 v146, 0xffff0000, v5
	v_lshlrev_b32_e32 v144, 16, v9
	v_and_b32_e32 v147, 0xffff0000, v9
	v_mul_f32_e32 v148, v133, v142
	v_mul_f32_e32 v149, v133, v145
	v_fmac_f32_e32 v148, v134, v143
	v_fmac_f32_e32 v149, v134, v146
	v_fmac_f32_e32 v148, v135, v144
	v_fmac_f32_e32 v149, v135, v147
	v_cvt_pk_bf16_f32 v161, v148, v149
	v_lshlrev_b32_e32 v142, 16, v2
	v_and_b32_e32 v145, 0xffff0000, v2
	v_lshlrev_b32_e32 v143, 16, v6
	v_and_b32_e32 v146, 0xffff0000, v6
	v_lshlrev_b32_e32 v144, 16, v10
	v_and_b32_e32 v147, 0xffff0000, v10
	v_mul_f32_e32 v148, v133, v142
	v_mul_f32_e32 v149, v133, v145
	v_fmac_f32_e32 v148, v134, v143
	v_fmac_f32_e32 v149, v134, v146
	v_fmac_f32_e32 v148, v135, v144
	v_fmac_f32_e32 v149, v135, v147
	v_cvt_pk_bf16_f32 v162, v148, v149
	v_lshlrev_b32_e32 v142, 16, v3
	v_and_b32_e32 v145, 0xffff0000, v3
	v_lshlrev_b32_e32 v143, 16, v7
	v_and_b32_e32 v146, 0xffff0000, v7
	v_lshlrev_b32_e32 v144, 16, v11
	v_and_b32_e32 v147, 0xffff0000, v11
	v_mul_f32_e32 v148, v133, v142
	v_mul_f32_e32 v149, v133, v145
	v_fmac_f32_e32 v148, v134, v143
	v_fmac_f32_e32 v149, v134, v146
	v_fmac_f32_e32 v148, v135, v144
	v_fmac_f32_e32 v149, v135, v147
	v_cvt_pk_bf16_f32 v163, v148, v149
	s_add_u32 s26, s24, 0x2000000
	s_addc_u32 s27, s25, 0
	global_store_dwordx4 v128, v[160:163], s[26:27]
	s_waitcnt vmcnt(43)
	v_max3_f32 v132, v28, v29, v30
	v_sub_f32_e32 v133, v28, v132
	v_sub_f32_e32 v134, v29, v132
	v_sub_f32_e32 v135, v30, v132
	v_mul_f32_e32 v133, 0x3fb8aa3b, v133
	v_mul_f32_e32 v134, 0x3fb8aa3b, v134
	v_mul_f32_e32 v135, 0x3fb8aa3b, v135
	v_exp_f32_e32 v133, v133
	v_exp_f32_e32 v134, v134
	v_exp_f32_e32 v135, v135
	s_nop 0
	v_add_f32_e32 v136, v133, v134
	v_add_f32_e32 v136, v135, v136
	v_div_scale_f32 v137, s[28:29], v136, v136, 1.0
	v_rcp_f32_e32 v138, v137
	v_div_scale_f32 v139, vcc, 1.0, v136, 1.0
	s_nop 0
	v_fma_f32 v140, -v137, v138, 1.0
	v_fmac_f32_e32 v138, v140, v138
	v_mul_f32_e32 v141, v139, v138
	v_fma_f32 v140, -v137, v141, v139
	v_fmac_f32_e32 v141, v140, v138
	v_fma_f32 v137, -v137, v141, v139
	v_div_fmas_f32 v137, v137, v138, v141
	v_div_fixup_f32 v136, v137, v136, 1.0
	v_mul_f32_e32 v133, v133, v136
	v_mul_f32_e32 v134, v134, v136
	v_mul_f32_e32 v135, v135, v136
	v_lshlrev_b32_e32 v142, 16, v16
	v_and_b32_e32 v145, 0xffff0000, v16
	v_lshlrev_b32_e32 v143, 16, v20
	v_and_b32_e32 v146, 0xffff0000, v20
	v_lshlrev_b32_e32 v144, 16, v24
	v_and_b32_e32 v147, 0xffff0000, v24
	v_mul_f32_e32 v148, v133, v142
	v_mul_f32_e32 v149, v133, v145
	v_fmac_f32_e32 v148, v134, v143
	v_fmac_f32_e32 v149, v134, v146
	v_fmac_f32_e32 v148, v135, v144
	v_fmac_f32_e32 v149, v135, v147
	v_cvt_pk_bf16_f32 v164, v148, v149
	v_lshlrev_b32_e32 v142, 16, v17
	v_and_b32_e32 v145, 0xffff0000, v17
	v_lshlrev_b32_e32 v143, 16, v21
	v_and_b32_e32 v146, 0xffff0000, v21
	v_lshlrev_b32_e32 v144, 16, v25
	v_and_b32_e32 v147, 0xffff0000, v25
	v_mul_f32_e32 v148, v133, v142
	v_mul_f32_e32 v149, v133, v145
	v_fmac_f32_e32 v148, v134, v143
	v_fmac_f32_e32 v149, v134, v146
	v_fmac_f32_e32 v148, v135, v144
	v_fmac_f32_e32 v149, v135, v147
	v_cvt_pk_bf16_f32 v165, v148, v149
	v_lshlrev_b32_e32 v142, 16, v18
	v_and_b32_e32 v145, 0xffff0000, v18
	v_lshlrev_b32_e32 v143, 16, v22
	v_and_b32_e32 v146, 0xffff0000, v22
	v_lshlrev_b32_e32 v144, 16, v26
	v_and_b32_e32 v147, 0xffff0000, v26
	v_mul_f32_e32 v148, v133, v142
	v_mul_f32_e32 v149, v133, v145
	v_fmac_f32_e32 v148, v134, v143
	v_fmac_f32_e32 v149, v134, v146
	v_fmac_f32_e32 v148, v135, v144
	v_fmac_f32_e32 v149, v135, v147
	v_cvt_pk_bf16_f32 v166, v148, v149
	v_lshlrev_b32_e32 v142, 16, v19
	v_and_b32_e32 v145, 0xffff0000, v19
	v_lshlrev_b32_e32 v143, 16, v23
	v_and_b32_e32 v146, 0xffff0000, v23
	v_lshlrev_b32_e32 v144, 16, v27
	v_and_b32_e32 v147, 0xffff0000, v27
	v_mul_f32_e32 v148, v133, v142
	v_mul_f32_e32 v149, v133, v145
	v_fmac_f32_e32 v148, v134, v143
	v_fmac_f32_e32 v149, v134, v146
	v_fmac_f32_e32 v148, v135, v144
	v_fmac_f32_e32 v149, v135, v147
	v_cvt_pk_bf16_f32 v167, v148, v149
	s_add_u32 s26, s24, 0x2200000
	s_addc_u32 s27, s25, 0
	global_store_dwordx4 v128, v[164:167], s[26:27]
	s_waitcnt vmcnt(37)
; __device__ __forceinline__ float bf_lo(unsigned w) { return __uint_as_float(w << 16); }
; __device__ __forceinline__ float bf_hi(unsigned w) { return __uint_as_float(w & 0xffff0000u); }
; __device__ __forceinline__ unsigned pk2(float lo, float hi) { return pg8::cvt_pk_bf16(lo, hi); }
; __device__ __forceinline__ void merge_rows(const Args& a, int gw, int NGW, int lane) {
;     const bf16* OG = (const bf16*)(a.ws + WS_OG); const float* LSE = (const float*)(a.ws + WS_LSE); bf16* YAT = (bf16*)(a.ws + WS_YAT);
;     const int hh = lane >> 4;
;     for (int mb = gw; mb < MT; mb += 4 * NGW) {
;         float l[4][3]; v2u o[4][3];
; #pragma unroll
;         for (int r = 0; r < 4; ++r) { const int m = mb + r * NGW; const int mc = m < MT ? m : mb;
; #pragma unroll
;             for (int g = 0; g < 3; ++g) { l[r][g] = LSE[((size_t)g * MT + mc) * 4 + hh]; o[r][g] = *(const v2u*)(OG + ((size_t)g * MT + mc) * 256 + 4 * lane); } }
; #pragma unroll
;         for (int r = 0; r < 4; ++r) { const int m = mb + r * NGW; if (m < MT) {
;             const float mxl = fmaxf(l[r][0], fmaxf(l[r][1], l[r][2]));
;             float a0 = __expf(l[r][0] - mxl), a1 = __expf(l[r][1] - mxl), a2 = __expf(l[r][2] - mxl); const float is = 1.0f / (a0 + a1 + a2); a0 *= is; a1 *= is; a2 *= is;
;             const v2u o0 = o[r][0], o1 = o[r][1], o2 = o[r][2];
;             v2u w;
;             w.x = pk2(a0 * pg8::bf_lo(o0.x) + a1 * pg8::bf_lo(o1.x) + a2 * pg8::bf_lo(o2.x), a0 * pg8::bf_hi(o0.x) + a1 * pg8::bf_hi(o1.x) + a2 * pg8::bf_hi(o2.x));
;             w.y = pk2(a0 * pg8::bf_lo(o0.y) + a1 * pg8::bf_lo(o1.y) + a2 * pg8::bf_lo(o2.y), a0 * pg8::bf_hi(o0.y) + a1 * pg8::bf_hi(o1.y) + a2 * pg8::bf_hi(o2.y));
;             *(v2u*)(YAT + (size_t)m * 256 + 4 * lane) = w; } }
;     }
; }
	v_max3_f32 v132, v44, v45, v46
	v_sub_f32_e32 v133, v44, v132
	v_sub_f32_e32 v134, v45, v132
	v_sub_f32_e32 v135, v46, v132
	v_mul_f32_e32 v133, 0x3fb8aa3b, v133
	v_mul_f32_e32 v134, 0x3fb8aa3b, v134
	v_mul_f32_e32 v135, 0x3fb8aa3b, v135
	v_exp_f32_e32 v133, v133
	v_exp_f32_e32 v134, v134
	v_exp_f32_e32 v135, v135
	s_nop 0
	v_add_f32_e32 v136, v133, v134
	v_add_f32_e32 v136, v135, v136
	v_div_scale_f32 v137, s[28:29], v136, v136, 1.0
	v_rcp_f32_e32 v138, v137
	v_div_scale_f32 v139, vcc, 1.0, v136, 1.0
	s_nop 0
	v_fma_f32 v140, -v137, v138, 1.0
	v_fmac_f32_e32 v138, v140, v138
	v_mul_f32_e32 v141, v139, v138
	v_fma_f32 v140, -v137, v141, v139
	v_fmac_f32_e32 v141, v140, v138
	v_fma_f32 v137, -v137, v141, v139
	v_div_fmas_f32 v137, v137, v138, v141
	v_div_fixup_f32 v136, v137, v136, 1.0
	v_mul_f32_e32 v133, v133, v136
	v_mul_f32_e32 v134, v134, v136
	v_mul_f32_e32 v135, v135, v136
	v_lshlrev_b32_e32 v142, 16, v32
	v_and_b32_e32 v145, 0xffff0000, v32
	v_lshlrev_b32_e32 v143, 16, v36
	v_and_b32_e32 v146, 0xffff0000, v36
	v_lshlrev_b32_e32 v144, 16, v40
	v_and_b32_e32 v147, 0xffff0000, v40
	v_mul_f32_e32 v148, v133, v142
	v_mul_f32_e32 v149, v133, v145
	v_fmac_f32_e32 v148, v134, v143
	v_fmac_f32_e32 v149, v134, v146
	v_fmac_f32_e32 v148, v135, v144
	v_fmac_f32_e32 v149, v135, v147
	v_cvt_pk_bf16_f32 v160, v148, v149
	v_lshlrev_b32_e32 v142, 16, v33
	v_and_b32_e32 v145, 0xffff0000, v33
	v_lshlrev_b32_e32 v143, 16, v37
	v_and_b32_e32 v146, 0xffff0000, v37
	v_lshlrev_b32_e32 v144, 16, v41
	v_and_b32_e32 v147, 0xffff0000, v41
	v_mul_f32_e32 v148, v133, v142
	v_mul_f32_e32 v149, v133, v145
	v_fmac_f32_e32 v148, v134, v143
	v_fmac_f32_e32 v149, v134, v146
	v_fmac_f32_e32 v148, v135, v144
	v_fmac_f32_e32 v149, v135, v147
	v_cvt_pk_bf16_f32 v161, v148, v149
	v_lshlrev_b32_e32 v142, 16, v34
	v_and_b32_e32 v145, 0xffff0000, v34
	v_lshlrev_b32_e32 v143, 16, v38
	v_and_b32_e32 v146, 0xffff0000, v38
	v_lshlrev_b32_e32 v144, 16, v42
	v_and_b32_e32 v147, 0xffff0000, v42
	v_mul_f32_e32 v148, v133, v142
	v_mul_f32_e32 v149, v133, v145
	v_fmac_f32_e32 v148, v134, v143
	v_fmac_f32_e32 v149, v134, v146
	v_fmac_f32_e32 v148, v135, v144
	v_fmac_f32_e32 v149, v135, v147
	v_cvt_pk_bf16_f32 v162, v148, v149
	v_lshlrev_b32_e32 v142, 16, v35
	v_and_b32_e32 v145, 0xffff0000, v35
	v_lshlrev_b32_e32 v143, 16, v39
	v_and_b32_e32 v146, 0xffff0000, v39
	v_lshlrev_b32_e32 v144, 16, v43
	v_and_b32_e32 v147, 0xffff0000, v43
	v_mul_f32_e32 v148, v133, v142
	v_mul_f32_e32 v149, v133, v145
	v_fmac_f32_e32 v148, v134, v143
	v_fmac_f32_e32 v149, v134, v146
	v_fmac_f32_e32 v148, v135, v144
	v_fmac_f32_e32 v149, v135, v147
	v_cvt_pk_bf16_f32 v163, v148, v149
	s_add_u32 s26, s24, 0x2400000
	s_addc_u32 s27, s25, 0
	global_store_dwordx4 v128, v[160:163], s[26:27]
	s_waitcnt vmcnt(31)
	v_max3_f32 v132, v60, v61, v62
	v_sub_f32_e32 v133, v60, v132
	v_sub_f32_e32 v134, v61, v132
	v_sub_f32_e32 v135, v62, v132
	v_mul_f32_e32 v133, 0x3fb8aa3b, v133
	v_mul_f32_e32 v134, 0x3fb8aa3b, v134
	v_mul_f32_e32 v135, 0x3fb8aa3b, v135
	v_exp_f32_e32 v133, v133
	v_exp_f32_e32 v134, v134
	v_exp_f32_e32 v135, v135
	s_nop 0
	v_add_f32_e32 v136, v133, v134
	v_add_f32_e32 v136, v135, v136
	v_div_scale_f32 v137, s[28:29], v136, v136, 1.0
	v_rcp_f32_e32 v138, v137
	v_div_scale_f32 v139, vcc, 1.0, v136, 1.0
	s_nop 0
	v_fma_f32 v140, -v137, v138, 1.0
	v_fmac_f32_e32 v138, v140, v138
	v_mul_f32_e32 v141, v139, v138
	v_fma_f32 v140, -v137, v141, v139
	v_fmac_f32_e32 v141, v140, v138
	v_fma_f32 v137, -v137, v141, v139
	v_div_fmas_f32 v137, v137, v138, v141
	v_div_fixup_f32 v136, v137, v136, 1.0
	v_mul_f32_e32 v133, v133, v136
	v_mul_f32_e32 v134, v134, v136
	v_mul_f32_e32 v135, v135, v136
	v_lshlrev_b32_e32 v142, 16, v48
	v_and_b32_e32 v145, 0xffff0000, v48
	v_lshlrev_b32_e32 v143, 16, v52
	v_and_b32_e32 v146, 0xffff0000, v52
	v_lshlrev_b32_e32 v144, 16, v56
	v_and_b32_e32 v147, 0xffff0000, v56
	v_mul_f32_e32 v148, v133, v142
	v_mul_f32_e32 v149, v133, v145
	v_fmac_f32_e32 v148, v134, v143
	v_fmac_f32_e32 v149, v134, v146
	v_fmac_f32_e32 v148, v135, v144
	v_fmac_f32_e32 v149, v135, v147
	v_cvt_pk_bf16_f32 v164, v148, v149
	v_lshlrev_b32_e32 v142, 16, v49
	v_and_b32_e32 v145, 0xffff0000, v49
	v_lshlrev_b32_e32 v143, 16, v53
	v_and_b32_e32 v146, 0xffff0000, v53
	v_lshlrev_b32_e32 v144, 16, v57
	v_and_b32_e32 v147, 0xffff0000, v57
	v_mul_f32_e32 v148, v133, v142
	v_mul_f32_e32 v149, v133, v145
	v_fmac_f32_e32 v148, v134, v143
	v_fmac_f32_e32 v149, v134, v146
	v_fmac_f32_e32 v148, v135, v144
	v_fmac_f32_e32 v149, v135, v147
	v_cvt_pk_bf16_f32 v165, v148, v149
	v_lshlrev_b32_e32 v142, 16, v50
	v_and_b32_e32 v145, 0xffff0000, v50
	v_lshlrev_b32_e32 v143, 16, v54
	v_and_b32_e32 v146, 0xffff0000, v54
	v_lshlrev_b32_e32 v144, 16, v58
	v_and_b32_e32 v147, 0xffff0000, v58
	v_mul_f32_e32 v148, v133, v142
	v_mul_f32_e32 v149, v133, v145
	v_fmac_f32_e32 v148, v134, v143
	v_fmac_f32_e32 v149, v134, v146
	v_fmac_f32_e32 v148, v135, v144
	v_fmac_f32_e32 v149, v135, v147
	v_cvt_pk_bf16_f32 v166, v148, v149
	v_lshlrev_b32_e32 v142, 16, v51
	v_and_b32_e32 v145, 0xffff0000, v51
	v_lshlrev_b32_e32 v143, 16, v55
	v_and_b32_e32 v146, 0xffff0000, v55
	v_lshlrev_b32_e32 v144, 16, v59
	v_and_b32_e32 v147, 0xffff0000, v59
	v_mul_f32_e32 v148, v133, v142
	v_mul_f32_e32 v149, v133, v145
	v_fmac_f32_e32 v148, v134, v143
	v_fmac_f32_e32 v149, v134, v146
	v_fmac_f32_e32 v148, v135, v144
	v_fmac_f32_e32 v149, v135, v147
	v_cvt_pk_bf16_f32 v167, v148, v149
	s_add_u32 s26, s24, 0x2600000
	s_addc_u32 s27, s25, 0
	global_store_dwordx4 v128, v[164:167], s[26:27]
	s_waitcnt vmcnt(25)
; __device__ __forceinline__ float bf_lo(unsigned w) { return __uint_as_float(w << 16); }
; __device__ __forceinline__ float bf_hi(unsigned w) { return __uint_as_float(w & 0xffff0000u); }
; __device__ __forceinline__ unsigned pk2(float lo, float hi) { return pg8::cvt_pk_bf16(lo, hi); }
; __device__ __forceinline__ void merge_rows(const Args& a, int gw, int NGW, int lane) {
;     const bf16* OG = (const bf16*)(a.ws + WS_OG); const float* LSE = (const float*)(a.ws + WS_LSE); bf16* YAT = (bf16*)(a.ws + WS_YAT);
;     const int hh = lane >> 4;
;     for (int mb = gw; mb < MT; mb += 4 * NGW) {
;         float l[4][3]; v2u o[4][3];
; #pragma unroll
;         for (int r = 0; r < 4; ++r) { const int m = mb + r * NGW; const int mc = m < MT ? m : mb;
; #pragma unroll
;             for (int g = 0; g < 3; ++g) { l[r][g] = LSE[((size_t)g * MT + mc) * 4 + hh]; o[r][g] = *(const v2u*)(OG + ((size_t)g * MT + mc) * 256 + 4 * lane); } }
; #pragma unroll
;         for (int r = 0; r < 4; ++r) { const int m = mb + r * NGW; if (m < MT) {
;             const float mxl = fmaxf(l[r][0], fmaxf(l[r][1], l[r][2]));
;             float a0 = __expf(l[r][0] - mxl), a1 = __expf(l[r][1] - mxl), a2 = __expf(l[r][2] - mxl); const float is = 1.0f / (a0 + a1 + a2); a0 *= is; a1 *= is; a2 *= is;
;             const v2u o0 = o[r][0], o1 = o[r][1], o2 = o[r][2];
;             v2u w;
;             w.x = pk2(a0 * pg8::bf_lo(o0.x) + a1 * pg8::bf_lo(o1.x) + a2 * pg8::bf_lo(o2.x), a0 * pg8::bf_hi(o0.x) + a1 * pg8::bf_hi(o1.x) + a2 * pg8::bf_hi(o2.x));
;             w.y = pk2(a0 * pg8::bf_lo(o0.y) + a1 * pg8::bf_lo(o1.y) + a2 * pg8::bf_lo(o2.y), a0 * pg8::bf_hi(o0.y) + a1 * pg8::bf_hi(o1.y) + a2 * pg8::bf_hi(o2.y));
;             *(v2u*)(YAT + (size_t)m * 256 + 4 * lane) = w; } }
;     }
; }
	v_max3_f32 v132, v76, v77, v78
	v_sub_f32_e32 v133, v76, v132
	v_sub_f32_e32 v134, v77, v132
	v_sub_f32_e32 v135, v78, v132
	v_mul_f32_e32 v133, 0x3fb8aa3b, v133
	v_mul_f32_e32 v134, 0x3fb8aa3b, v134
	v_mul_f32_e32 v135, 0x3fb8aa3b, v135
	v_exp_f32_e32 v133, v133
	v_exp_f32_e32 v134, v134
	v_exp_f32_e32 v135, v135
	s_nop 0
	v_add_f32_e32 v136, v133, v134
	v_add_f32_e32 v136, v135, v136
	v_div_scale_f32 v137, s[28:29], v136, v136, 1.0
	v_rcp_f32_e32 v138, v137
	v_div_scale_f32 v139, vcc, 1.0, v136, 1.0
	s_nop 0
	v_fma_f32 v140, -v137, v138, 1.0
	v_fmac_f32_e32 v138, v140, v138
	v_mul_f32_e32 v141, v139, v138
	v_fma_f32 v140, -v137, v141, v139
	v_fmac_f32_e32 v141, v140, v138
	v_fma_f32 v137, -v137, v141, v139
	v_div_fmas_f32 v137, v137, v138, v141
	v_div_fixup_f32 v136, v137, v136, 1.0
	v_mul_f32_e32 v133, v133, v136
	v_mul_f32_e32 v134, v134, v136
	v_mul_f32_e32 v135, v135, v136
	v_lshlrev_b32_e32 v142, 16, v64
	v_and_b32_e32 v145, 0xffff0000, v64
	v_lshlrev_b32_e32 v143, 16, v68
	v_and_b32_e32 v146, 0xffff0000, v68
	v_lshlrev_b32_e32 v144, 16, v72
	v_and_b32_e32 v147, 0xffff0000, v72
	v_mul_f32_e32 v148, v133, v142
	v_mul_f32_e32 v149, v133, v145
	v_fmac_f32_e32 v148, v134, v143
	v_fmac_f32_e32 v149, v134, v146
	v_fmac_f32_e32 v148, v135, v144
	v_fmac_f32_e32 v149, v135, v147
	v_cvt_pk_bf16_f32 v160, v148, v149
	v_lshlrev_b32_e32 v142, 16, v65
	v_and_b32_e32 v145, 0xffff0000, v65
	v_lshlrev_b32_e32 v143, 16, v69
	v_and_b32_e32 v146, 0xffff0000, v69
	v_lshlrev_b32_e32 v144, 16, v73
	v_and_b32_e32 v147, 0xffff0000, v73
	v_mul_f32_e32 v148, v133, v142
	v_mul_f32_e32 v149, v133, v145
	v_fmac_f32_e32 v148, v134, v143
	v_fmac_f32_e32 v149, v134, v146
	v_fmac_f32_e32 v148, v135, v144
	v_fmac_f32_e32 v149, v135, v147
	v_cvt_pk_bf16_f32 v161, v148, v149
	v_lshlrev_b32_e32 v142, 16, v66
	v_and_b32_e32 v145, 0xffff0000, v66
	v_lshlrev_b32_e32 v143, 16, v70
	v_and_b32_e32 v146, 0xffff0000, v70
	v_lshlrev_b32_e32 v144, 16, v74
	v_and_b32_e32 v147, 0xffff0000, v74
	v_mul_f32_e32 v148, v133, v142
	v_mul_f32_e32 v149, v133, v145
	v_fmac_f32_e32 v148, v134, v143
	v_fmac_f32_e32 v149, v134, v146
	v_fmac_f32_e32 v148, v135, v144
	v_fmac_f32_e32 v149, v135, v147
	v_cvt_pk_bf16_f32 v162, v148, v149
	v_lshlrev_b32_e32 v142, 16, v67
	v_and_b32_e32 v145, 0xffff0000, v67
	v_lshlrev_b32_e32 v143, 16, v71
	v_and_b32_e32 v146, 0xffff0000, v71
	v_lshlrev_b32_e32 v144, 16, v75
	v_and_b32_e32 v147, 0xffff0000, v75
	v_mul_f32_e32 v148, v133, v142
	v_mul_f32_e32 v149, v133, v145
	v_fmac_f32_e32 v148, v134, v143
	v_fmac_f32_e32 v149, v134, v146
	v_fmac_f32_e32 v148, v135, v144
	v_fmac_f32_e32 v149, v135, v147
	v_cvt_pk_bf16_f32 v163, v148, v149
	s_add_u32 s26, s24, 0x2800000
	s_addc_u32 s27, s25, 0
	global_store_dwordx4 v128, v[160:163], s[26:27]
	s_waitcnt vmcnt(19)
	v_max3_f32 v132, v92, v93, v94
	v_sub_f32_e32 v133, v92, v132
	v_sub_f32_e32 v134, v93, v132
	v_sub_f32_e32 v135, v94, v132
	v_mul_f32_e32 v133, 0x3fb8aa3b, v133
	v_mul_f32_e32 v134, 0x3fb8aa3b, v134
	v_mul_f32_e32 v135, 0x3fb8aa3b, v135
	v_exp_f32_e32 v133, v133
	v_exp_f32_e32 v134, v134
	v_exp_f32_e32 v135, v135
	s_nop 0
	v_add_f32_e32 v136, v133, v134
	v_add_f32_e32 v136, v135, v136
	v_div_scale_f32 v137, s[28:29], v136, v136, 1.0
	v_rcp_f32_e32 v138, v137
	v_div_scale_f32 v139, vcc, 1.0, v136, 1.0
	s_nop 0
	v_fma_f32 v140, -v137, v138, 1.0
	v_fmac_f32_e32 v138, v140, v138
	v_mul_f32_e32 v141, v139, v138
	v_fma_f32 v140, -v137, v141, v139
	v_fmac_f32_e32 v141, v140, v138
	v_fma_f32 v137, -v137, v141, v139
	v_div_fmas_f32 v137, v137, v138, v141
	v_div_fixup_f32 v136, v137, v136, 1.0
	v_mul_f32_e32 v133, v133, v136
	v_mul_f32_e32 v134, v134, v136
	v_mul_f32_e32 v135, v135, v136
	v_lshlrev_b32_e32 v142, 16, v80
	v_and_b32_e32 v145, 0xffff0000, v80
	v_lshlrev_b32_e32 v143, 16, v84
	v_and_b32_e32 v146, 0xffff0000, v84
	v_lshlrev_b32_e32 v144, 16, v88
	v_and_b32_e32 v147, 0xffff0000, v88
	v_mul_f32_e32 v148, v133, v142
	v_mul_f32_e32 v149, v133, v145
	v_fmac_f32_e32 v148, v134, v143
	v_fmac_f32_e32 v149, v134, v146
	v_fmac_f32_e32 v148, v135, v144
	v_fmac_f32_e32 v149, v135, v147
	v_cvt_pk_bf16_f32 v164, v148, v149
	v_lshlrev_b32_e32 v142, 16, v81
	v_and_b32_e32 v145, 0xffff0000, v81
	v_lshlrev_b32_e32 v143, 16, v85
	v_and_b32_e32 v146, 0xffff0000, v85
	v_lshlrev_b32_e32 v144, 16, v89
	v_and_b32_e32 v147, 0xffff0000, v89
	v_mul_f32_e32 v148, v133, v142
	v_mul_f32_e32 v149, v133, v145
	v_fmac_f32_e32 v148, v134, v143
	v_fmac_f32_e32 v149, v134, v146
	v_fmac_f32_e32 v148, v135, v144
	v_fmac_f32_e32 v149, v135, v147
	v_cvt_pk_bf16_f32 v165, v148, v149
	v_lshlrev_b32_e32 v142, 16, v82
	v_and_b32_e32 v145, 0xffff0000, v82
	v_lshlrev_b32_e32 v143, 16, v86
	v_and_b32_e32 v146, 0xffff0000, v86
	v_lshlrev_b32_e32 v144, 16, v90
	v_and_b32_e32 v147, 0xffff0000, v90
	v_mul_f32_e32 v148, v133, v142
	v_mul_f32_e32 v149, v133, v145
	v_fmac_f32_e32 v148, v134, v143
	v_fmac_f32_e32 v149, v134, v146
	v_fmac_f32_e32 v148, v135, v144
	v_fmac_f32_e32 v149, v135, v147
	v_cvt_pk_bf16_f32 v166, v148, v149
	v_lshlrev_b32_e32 v142, 16, v83
	v_and_b32_e32 v145, 0xffff0000, v83
	v_lshlrev_b32_e32 v143, 16, v87
	v_and_b32_e32 v146, 0xffff0000, v87
	v_lshlrev_b32_e32 v144, 16, v91
	v_and_b32_e32 v147, 0xffff0000, v91
	v_mul_f32_e32 v148, v133, v142
	v_mul_f32_e32 v149, v133, v145
	v_fmac_f32_e32 v148, v134, v143
	v_fmac_f32_e32 v149, v134, v146
	v_fmac_f32_e32 v148, v135, v144
	v_fmac_f32_e32 v149, v135, v147
	v_cvt_pk_bf16_f32 v167, v148, v149
	s_add_u32 s26, s24, 0x2a00000
	s_addc_u32 s27, s25, 0
	global_store_dwordx4 v128, v[164:167], s[26:27]
	s_waitcnt vmcnt(13)
; __device__ __forceinline__ float bf_lo(unsigned w) { return __uint_as_float(w << 16); }
; __device__ __forceinline__ float bf_hi(unsigned w) { return __uint_as_float(w & 0xffff0000u); }
; __device__ __forceinline__ unsigned pk2(float lo, float hi) { return pg8::cvt_pk_bf16(lo, hi); }
; __device__ __forceinline__ void merge_rows(const Args& a, int gw, int NGW, int lane) {
;     const bf16* OG = (const bf16*)(a.ws + WS_OG); const float* LSE = (const float*)(a.ws + WS_LSE); bf16* YAT = (bf16*)(a.ws + WS_YAT);
;     const int hh = lane >> 4;
;     for (int mb = gw; mb < MT; mb += 4 * NGW) {
;         float l[4][3]; v2u o[4][3];
; #pragma unroll
;         for (int r = 0; r < 4; ++r) { const int m = mb + r * NGW; const int mc = m < MT ? m : mb;
; #pragma unroll
;             for (int g = 0; g < 3; ++g) { l[r][g] = LSE[((size_t)g * MT + mc) * 4 + hh]; o[r][g] = *(const v2u*)(OG + ((size_t)g * MT + mc) * 256 + 4 * lane); } }
; #pragma unroll
;         for (int r = 0; r < 4; ++r) { const int m = mb + r * NGW; if (m < MT) {
;             const float mxl = fmaxf(l[r][0], fmaxf(l[r][1], l[r][2]));
;             float a0 = __expf(l[r][0] - mxl), a1 = __expf(l[r][1] - mxl), a2 = __expf(l[r][2] - mxl); const float is = 1.0f / (a0 + a1 + a2); a0 *= is; a1 *= is; a2 *= is;
;             const v2u o0 = o[r][0], o1 = o[r][1], o2 = o[r][2];
;             v2u w;
;             w.x = pk2(a0 * pg8::bf_lo(o0.x) + a1 * pg8::bf_lo(o1.x) + a2 * pg8::bf_lo(o2.x), a0 * pg8::bf_hi(o0.x) + a1 * pg8::bf_hi(o1.x) + a2 * pg8::bf_hi(o2.x));
;             w.y = pk2(a0 * pg8::bf_lo(o0.y) + a1 * pg8::bf_lo(o1.y) + a2 * pg8::bf_lo(o2.y), a0 * pg8::bf_hi(o0.y) + a1 * pg8::bf_hi(o1.y) + a2 * pg8::bf_hi(o2.y));
;             *(v2u*)(YAT + (size_t)m * 256 + 4 * lane) = w; } }
;     }
; }
	v_max3_f32 v132, v108, v109, v110
	v_sub_f32_e32 v133, v108, v132
	v_sub_f32_e32 v134, v109, v132
	v_sub_f32_e32 v135, v110, v132
	v_mul_f32_e32 v133, 0x3fb8aa3b, v133
	v_mul_f32_e32 v134, 0x3fb8aa3b, v134
	v_mul_f32_e32 v135, 0x3fb8aa3b, v135
	v_exp_f32_e32 v133, v133
	v_exp_f32_e32 v134, v134
	v_exp_f32_e32 v135, v135
	s_nop 0
	v_add_f32_e32 v136, v133, v134
	v_add_f32_e32 v136, v135, v136
	v_div_scale_f32 v137, s[28:29], v136, v136, 1.0
	v_rcp_f32_e32 v138, v137
	v_div_scale_f32 v139, vcc, 1.0, v136, 1.0
	s_nop 0
	v_fma_f32 v140, -v137, v138, 1.0
	v_fmac_f32_e32 v138, v140, v138
	v_mul_f32_e32 v141, v139, v138
	v_fma_f32 v140, -v137, v141, v139
	v_fmac_f32_e32 v141, v140, v138
	v_fma_f32 v137, -v137, v141, v139
	v_div_fmas_f32 v137, v137, v138, v141
	v_div_fixup_f32 v136, v137, v136, 1.0
	v_mul_f32_e32 v133, v133, v136
	v_mul_f32_e32 v134, v134, v136
	v_mul_f32_e32 v135, v135, v136
	v_lshlrev_b32_e32 v142, 16, v96
	v_and_b32_e32 v145, 0xffff0000, v96
	v_lshlrev_b32_e32 v143, 16, v100
	v_and_b32_e32 v146, 0xffff0000, v100
	v_lshlrev_b32_e32 v144, 16, v104
	v_and_b32_e32 v147, 0xffff0000, v104
	v_mul_f32_e32 v148, v133, v142
	v_mul_f32_e32 v149, v133, v145
	v_fmac_f32_e32 v148, v134, v143
	v_fmac_f32_e32 v149, v134, v146
	v_fmac_f32_e32 v148, v135, v144
	v_fmac_f32_e32 v149, v135, v147
	v_cvt_pk_bf16_f32 v160, v148, v149
	v_lshlrev_b32_e32 v142, 16, v97
	v_and_b32_e32 v145, 0xffff0000, v97
	v_lshlrev_b32_e32 v143, 16, v101
	v_and_b32_e32 v146, 0xffff0000, v101
	v_lshlrev_b32_e32 v144, 16, v105
	v_and_b32_e32 v147, 0xffff0000, v105
	v_mul_f32_e32 v148, v133, v142
	v_mul_f32_e32 v149, v133, v145
	v_fmac_f32_e32 v148, v134, v143
	v_fmac_f32_e32 v149, v134, v146
	v_fmac_f32_e32 v148, v135, v144
	v_fmac_f32_e32 v149, v135, v147
	v_cvt_pk_bf16_f32 v161, v148, v149
	v_lshlrev_b32_e32 v142, 16, v98
	v_and_b32_e32 v145, 0xffff0000, v98
	v_lshlrev_b32_e32 v143, 16, v102
	v_and_b32_e32 v146, 0xffff0000, v102
	v_lshlrev_b32_e32 v144, 16, v106
	v_and_b32_e32 v147, 0xffff0000, v106
	v_mul_f32_e32 v148, v133, v142
	v_mul_f32_e32 v149, v133, v145
	v_fmac_f32_e32 v148, v134, v143
	v_fmac_f32_e32 v149, v134, v146
	v_fmac_f32_e32 v148, v135, v144
	v_fmac_f32_e32 v149, v135, v147
	v_cvt_pk_bf16_f32 v162, v148, v149
	v_lshlrev_b32_e32 v142, 16, v99
	v_and_b32_e32 v145, 0xffff0000, v99
	v_lshlrev_b32_e32 v143, 16, v103
	v_and_b32_e32 v146, 0xffff0000, v103
	v_lshlrev_b32_e32 v144, 16, v107
	v_and_b32_e32 v147, 0xffff0000, v107
	v_mul_f32_e32 v148, v133, v142
	v_mul_f32_e32 v149, v133, v145
	v_fmac_f32_e32 v148, v134, v143
	v_fmac_f32_e32 v149, v134, v146
	v_fmac_f32_e32 v148, v135, v144
	v_fmac_f32_e32 v149, v135, v147
	v_cvt_pk_bf16_f32 v163, v148, v149
	s_add_u32 s26, s24, 0x2c00000
	s_addc_u32 s27, s25, 0
	global_store_dwordx4 v128, v[160:163], s[26:27]
	s_waitcnt vmcnt(7)
	v_max3_f32 v132, v124, v125, v126
	v_sub_f32_e32 v133, v124, v132
	v_sub_f32_e32 v134, v125, v132
	v_sub_f32_e32 v135, v126, v132
	v_mul_f32_e32 v133, 0x3fb8aa3b, v133
	v_mul_f32_e32 v134, 0x3fb8aa3b, v134
	v_mul_f32_e32 v135, 0x3fb8aa3b, v135
	v_exp_f32_e32 v133, v133
	v_exp_f32_e32 v134, v134
	v_exp_f32_e32 v135, v135
	s_nop 0
	v_add_f32_e32 v136, v133, v134
	v_add_f32_e32 v136, v135, v136
	v_div_scale_f32 v137, s[28:29], v136, v136, 1.0
	v_rcp_f32_e32 v138, v137
	v_div_scale_f32 v139, vcc, 1.0, v136, 1.0
	s_nop 0
	v_fma_f32 v140, -v137, v138, 1.0
	v_fmac_f32_e32 v138, v140, v138
	v_mul_f32_e32 v141, v139, v138
	v_fma_f32 v140, -v137, v141, v139
	v_fmac_f32_e32 v141, v140, v138
	v_fma_f32 v137, -v137, v141, v139
	v_div_fmas_f32 v137, v137, v138, v141
	v_div_fixup_f32 v136, v137, v136, 1.0
	v_mul_f32_e32 v133, v133, v136
	v_mul_f32_e32 v134, v134, v136
	v_mul_f32_e32 v135, v135, v136
	v_lshlrev_b32_e32 v142, 16, v112
	v_and_b32_e32 v145, 0xffff0000, v112
	v_lshlrev_b32_e32 v143, 16, v116
	v_and_b32_e32 v146, 0xffff0000, v116
	v_lshlrev_b32_e32 v144, 16, v120
	v_and_b32_e32 v147, 0xffff0000, v120
	v_mul_f32_e32 v148, v133, v142
	v_mul_f32_e32 v149, v133, v145
	v_fmac_f32_e32 v148, v134, v143
	v_fmac_f32_e32 v149, v134, v146
	v_fmac_f32_e32 v148, v135, v144
	v_fmac_f32_e32 v149, v135, v147
	v_cvt_pk_bf16_f32 v164, v148, v149
	v_lshlrev_b32_e32 v142, 16, v113
	v_and_b32_e32 v145, 0xffff0000, v113
	v_lshlrev_b32_e32 v143, 16, v117
	v_and_b32_e32 v146, 0xffff0000, v117
	v_lshlrev_b32_e32 v144, 16, v121
	v_and_b32_e32 v147, 0xffff0000, v121
	v_mul_f32_e32 v148, v133, v142
	v_mul_f32_e32 v149, v133, v145
	v_fmac_f32_e32 v148, v134, v143
	v_fmac_f32_e32 v149, v134, v146
	v_fmac_f32_e32 v148, v135, v144
	v_fmac_f32_e32 v149, v135, v147
	v_cvt_pk_bf16_f32 v165, v148, v149
	v_lshlrev_b32_e32 v142, 16, v114
	v_and_b32_e32 v145, 0xffff0000, v114
	v_lshlrev_b32_e32 v143, 16, v118
	v_and_b32_e32 v146, 0xffff0000, v118
	v_lshlrev_b32_e32 v144, 16, v122
	v_and_b32_e32 v147, 0xffff0000, v122
	v_mul_f32_e32 v148, v133, v142
	v_mul_f32_e32 v149, v133, v145
	v_fmac_f32_e32 v148, v134, v143
	v_fmac_f32_e32 v149, v134, v146
	v_fmac_f32_e32 v148, v135, v144
	v_fmac_f32_e32 v149, v135, v147
	v_cvt_pk_bf16_f32 v166, v148, v149
	v_lshlrev_b32_e32 v142, 16, v115
	v_and_b32_e32 v145, 0xffff0000, v115
	v_lshlrev_b32_e32 v143, 16, v119
	v_and_b32_e32 v146, 0xffff0000, v119
	v_lshlrev_b32_e32 v144, 16, v123
	v_and_b32_e32 v147, 0xffff0000, v123
	v_mul_f32_e32 v148, v133, v142
	v_mul_f32_e32 v149, v133, v145
	v_fmac_f32_e32 v148, v134, v143
	v_fmac_f32_e32 v149, v134, v146
	v_fmac_f32_e32 v148, v135, v144
	v_fmac_f32_e32 v149, v135, v147
	v_cvt_pk_bf16_f32 v167, v148, v149
	s_add_u32 s26, s24, 0x2e00000
	s_addc_u32 s27, s25, 0
	global_store_dwordx4 v128, v[164:167], s[26:27]
	s_branch .LBB0_467
